# accumulator clearing via v_pk_mov_b32 pairs; SwiGLU epilogue rstd LDS reads hoisted to the epilogue head
# speedup vs baseline: 1.0372x; 1.0044x over previous
; template <class Epi, class Ord>
; __device__ __forceinline__ void gemm_phase(LAS unsigned char* lds, const Gemm g, const Ord& S, const Epi& E) {
;     ...
; #pragma unroll
;         for (int a = 0; a < 2; ++a)
; #pragma unroll
;             for (int b = 0; b < 2; ++b)
; #pragma unroll
;                 for (int m = 0; m < 4; ++m)
; #pragma unroll
;                     for (int n = 0; n < 2; ++n) acc[a][b][m][n] = (f32x4){0.f, 0.f, 0.f, 0.f};
.LBB0_165:
	v_mov_b32_e32 v123, 0
	v_mov_b32_e32 v122, 0
	s_andn2_b64 vcc, exec, s[18:19]
	v_pk_mov_b32 v[120:121], v[122:123], v[122:123]
	v_pk_mov_b32 v[126:127], v[122:123], v[122:123]
	v_pk_mov_b32 v[124:125], v[122:123], v[122:123]
	v_pk_mov_b32 v[110:111], v[122:123], v[122:123]
	v_pk_mov_b32 v[108:109], v[122:123], v[122:123]
	v_pk_mov_b32 v[106:107], v[122:123], v[122:123]
	v_pk_mov_b32 v[104:105], v[122:123], v[122:123]
	v_pk_mov_b32 v[94:95], v[122:123], v[122:123]
	v_pk_mov_b32 v[92:93], v[122:123], v[122:123]
	v_pk_mov_b32 v[90:91], v[122:123], v[122:123]
	v_pk_mov_b32 v[88:89], v[122:123], v[122:123]
	v_pk_mov_b32 v[78:79], v[122:123], v[122:123]
	v_pk_mov_b32 v[76:77], v[122:123], v[122:123]
	v_pk_mov_b32 v[74:75], v[122:123], v[122:123]
	v_pk_mov_b32 v[72:73], v[122:123], v[122:123]
	v_pk_mov_b32 v[118:119], v[122:123], v[122:123]
	v_pk_mov_b32 v[116:117], v[122:123], v[122:123]
	v_pk_mov_b32 v[114:115], v[122:123], v[122:123]
	v_pk_mov_b32 v[112:113], v[122:123], v[122:123]
	v_pk_mov_b32 v[102:103], v[122:123], v[122:123]
	v_pk_mov_b32 v[100:101], v[122:123], v[122:123]
	v_pk_mov_b32 v[98:99], v[122:123], v[122:123]
	v_pk_mov_b32 v[96:97], v[122:123], v[122:123]
	v_pk_mov_b32 v[86:87], v[122:123], v[122:123]
	v_pk_mov_b32 v[84:85], v[122:123], v[122:123]
	v_pk_mov_b32 v[82:83], v[122:123], v[122:123]
	v_pk_mov_b32 v[80:81], v[122:123], v[122:123]
	v_pk_mov_b32 v[70:71], v[122:123], v[122:123]
	v_pk_mov_b32 v[68:69], v[122:123], v[122:123]
	v_pk_mov_b32 v[66:67], v[122:123], v[122:123]
	v_pk_mov_b32 v[64:65], v[122:123], v[122:123]
	v_pk_mov_b32 v[62:63], v[122:123], v[122:123]
	v_pk_mov_b32 v[60:61], v[122:123], v[122:123]
	v_pk_mov_b32 v[58:59], v[122:123], v[122:123]
	v_pk_mov_b32 v[56:57], v[122:123], v[122:123]
	v_pk_mov_b32 v[46:47], v[122:123], v[122:123]
	v_pk_mov_b32 v[44:45], v[122:123], v[122:123]
	v_pk_mov_b32 v[42:43], v[122:123], v[122:123]
	v_pk_mov_b32 v[40:41], v[122:123], v[122:123]
	v_pk_mov_b32 v[30:31], v[122:123], v[122:123]
	v_pk_mov_b32 v[28:29], v[122:123], v[122:123]
	v_pk_mov_b32 v[26:27], v[122:123], v[122:123]
	v_pk_mov_b32 v[24:25], v[122:123], v[122:123]
	v_pk_mov_b32 v[14:15], v[122:123], v[122:123]
	v_pk_mov_b32 v[12:13], v[122:123], v[122:123]
	v_pk_mov_b32 v[10:11], v[122:123], v[122:123]
	v_pk_mov_b32 v[8:9], v[122:123], v[122:123]
	v_pk_mov_b32 v[54:55], v[122:123], v[122:123]
	v_pk_mov_b32 v[52:53], v[122:123], v[122:123]
	v_pk_mov_b32 v[50:51], v[122:123], v[122:123]
	v_pk_mov_b32 v[48:49], v[122:123], v[122:123]
	v_pk_mov_b32 v[38:39], v[122:123], v[122:123]
	v_pk_mov_b32 v[36:37], v[122:123], v[122:123]
	v_pk_mov_b32 v[34:35], v[122:123], v[122:123]
	v_pk_mov_b32 v[32:33], v[122:123], v[122:123]
	v_pk_mov_b32 v[22:23], v[122:123], v[122:123]
	v_pk_mov_b32 v[20:21], v[122:123], v[122:123]
	v_pk_mov_b32 v[18:19], v[122:123], v[122:123]
	v_pk_mov_b32 v[16:17], v[122:123], v[122:123]
	v_pk_mov_b32 v[6:7], v[122:123], v[122:123]
	v_pk_mov_b32 v[4:5], v[122:123], v[122:123]
	v_pk_mov_b32 v[2:3], v[122:123], v[122:123]
	v_pk_mov_b32 v[0:1], v[122:123], v[122:123]
	s_cbranch_vccnz .LBB0_154
	s_add_u32 s46, s46, 0x100
	s_addc_u32 s47, s47, 0
	s_add_u32 s52, s52, 0x100
	v_mov_b32_e32 v0, 0
	v_mov_b32_e32 v1, 0
	s_addc_u32 s53, s53, 0
	s_mov_b32 s12, 0
	v_pk_mov_b32 v[2:3], v[0:1], v[0:1]
	v_pk_mov_b32 v[4:5], v[0:1], v[0:1]
	v_pk_mov_b32 v[6:7], v[0:1], v[0:1]
	v_pk_mov_b32 v[16:17], v[0:1], v[0:1]
	v_pk_mov_b32 v[18:19], v[0:1], v[0:1]
	v_pk_mov_b32 v[20:21], v[0:1], v[0:1]
	v_pk_mov_b32 v[22:23], v[0:1], v[0:1]
	v_pk_mov_b32 v[32:33], v[0:1], v[0:1]
	v_pk_mov_b32 v[34:35], v[0:1], v[0:1]
	v_pk_mov_b32 v[36:37], v[0:1], v[0:1]
	v_pk_mov_b32 v[38:39], v[0:1], v[0:1]
	v_pk_mov_b32 v[48:49], v[0:1], v[0:1]
	v_pk_mov_b32 v[50:51], v[0:1], v[0:1]
	v_pk_mov_b32 v[52:53], v[0:1], v[0:1]
	v_pk_mov_b32 v[54:55], v[0:1], v[0:1]
	v_pk_mov_b32 v[8:9], v[0:1], v[0:1]
	v_pk_mov_b32 v[10:11], v[0:1], v[0:1]
	v_pk_mov_b32 v[12:13], v[0:1], v[0:1]
	v_pk_mov_b32 v[14:15], v[0:1], v[0:1]
	v_pk_mov_b32 v[24:25], v[0:1], v[0:1]
	v_pk_mov_b32 v[26:27], v[0:1], v[0:1]
	v_pk_mov_b32 v[28:29], v[0:1], v[0:1]
	v_pk_mov_b32 v[30:31], v[0:1], v[0:1]
	v_pk_mov_b32 v[40:41], v[0:1], v[0:1]
	v_pk_mov_b32 v[42:43], v[0:1], v[0:1]
	v_pk_mov_b32 v[44:45], v[0:1], v[0:1]
	v_pk_mov_b32 v[46:47], v[0:1], v[0:1]
	v_pk_mov_b32 v[56:57], v[0:1], v[0:1]
	v_pk_mov_b32 v[58:59], v[0:1], v[0:1]
	v_pk_mov_b32 v[60:61], v[0:1], v[0:1]
	v_pk_mov_b32 v[62:63], v[0:1], v[0:1]
	v_pk_mov_b32 v[64:65], v[0:1], v[0:1]
	v_pk_mov_b32 v[66:67], v[0:1], v[0:1]
	v_pk_mov_b32 v[68:69], v[0:1], v[0:1]
	v_pk_mov_b32 v[70:71], v[0:1], v[0:1]
	v_pk_mov_b32 v[80:81], v[0:1], v[0:1]
	v_pk_mov_b32 v[82:83], v[0:1], v[0:1]
	v_pk_mov_b32 v[84:85], v[0:1], v[0:1]
	v_pk_mov_b32 v[86:87], v[0:1], v[0:1]
	v_pk_mov_b32 v[96:97], v[0:1], v[0:1]
	v_pk_mov_b32 v[98:99], v[0:1], v[0:1]
	v_pk_mov_b32 v[100:101], v[0:1], v[0:1]
	v_pk_mov_b32 v[102:103], v[0:1], v[0:1]
	v_pk_mov_b32 v[112:113], v[0:1], v[0:1]
	v_pk_mov_b32 v[114:115], v[0:1], v[0:1]
	v_pk_mov_b32 v[116:117], v[0:1], v[0:1]
	v_pk_mov_b32 v[118:119], v[0:1], v[0:1]
	v_pk_mov_b32 v[72:73], v[0:1], v[0:1]
	v_pk_mov_b32 v[74:75], v[0:1], v[0:1]
	v_pk_mov_b32 v[76:77], v[0:1], v[0:1]
	v_pk_mov_b32 v[78:79], v[0:1], v[0:1]
	v_pk_mov_b32 v[88:89], v[0:1], v[0:1]
	v_pk_mov_b32 v[90:91], v[0:1], v[0:1]
	v_pk_mov_b32 v[92:93], v[0:1], v[0:1]
	v_pk_mov_b32 v[94:95], v[0:1], v[0:1]
	v_pk_mov_b32 v[104:105], v[0:1], v[0:1]
	v_pk_mov_b32 v[106:107], v[0:1], v[0:1]
	v_pk_mov_b32 v[108:109], v[0:1], v[0:1]
	v_pk_mov_b32 v[110:111], v[0:1], v[0:1]
	v_pk_mov_b32 v[124:125], v[0:1], v[0:1]
	v_pk_mov_b32 v[126:127], v[0:1], v[0:1]
	v_pk_mov_b32 v[120:121], v[0:1], v[0:1]
	v_pk_mov_b32 v[122:123], v[0:1], v[0:1]

; __device__ __forceinline__ unsigned cvt_pk_bf16(float lo, float hi) { const f32x2 v = {lo, hi}; return __builtin_bit_cast(unsigned, __builtin_convertvector(v, bfx2_t)); }
;     __device__ __forceinline__ void operator()(const AccT& acc, const Unit& u, int ui, int wr, int wc, int fr, int fq) const {
;         const int col = u.pn * 128 + wc * 32 + 8 * fq;
; #pragma unroll
;         for (int ai = 0; ai < 2; ++ai)
; #pragma unroll
;             for (int m = 0; m < 4; ++m) {
;                 const int rl = ai * 128 + wr * 64 + m * 16 + fr; const float r = rs[((u.pm >> 3) & 3) * 256 + rl];
;                 const float nr = -1.4426950408889634f * r, r2 = r * r;
;                 unsigned w[4];
; #pragma unroll
;                 for (int n = 0; n < 2; ++n)
; #pragma unroll
;                     for (int hlf = 0; hlf < 2; ++hlf) {
;                         const f32x2 a = {acc[ai][0][m][n][2 * hlf], acc[ai][0][m][n][2 * hlf + 1]}, b = {acc[ai][1][m][n][2 * hlf], acc[ai][1][m][n][2 * hlf + 1]};
;                         const f32x2 t = a * nr;
;                         f32x2 d; d.x = __builtin_amdgcn_exp2f(t.x); d.y = __builtin_amdgcn_exp2f(t.y); d = d + 1.0f;
;                         f32x2 q; q.x = __builtin_amdgcn_rcpf(d.x); q.y = __builtin_amdgcn_rcpf(d.y);
;                         const f32x2 o = ((a * b) * r2) * q;
;                         w[n * 2 + hlf] = cvt_pk_bf16(o.x, o.y);
;                     }
;                 u32x4 wv; wv.x = w[0]; wv.y = w[1]; wv.z = w[2]; wv.w = w[3];
;                 *GP(u32x4, O + (size_t)(u.pm * 256 + rl) * FF + col) = wv;
.LBB0_227:
	s_lshl_b32 s13, s78, 7
	s_and_b32 s13, s13, 0xc00
	v_add_u32_e32 v140, s13, v138
	ds_read2_b32 v[144:145], v140 offset1:16
	ds_read2_b32 v[174:175], v140 offset0:32 offset1:48
	ds_read2_b32 v[176:177], v140 offset0:128 offset1:144
	ds_read2_b32 v[178:179], v140 offset0:160 offset1:176
	v_pk_mul_f32 v[126:127], v[126:127], v[122:123]
	v_pk_mul_f32 v[118:119], v[118:119], v[114:115]
	v_lshl_or_b32 v142, s79, 7, v137
	s_lshl_b32 s12, s78, 8
	s_waitcnt lgkmcnt(0)
	v_mul_f32_e32 v146, 0xbfb8aa3b, v144
	v_pk_mul_f32 v[148:149], v[120:121], v[146:147] op_sel_hi:[1,0]
	v_pk_mul_f32 v[122:123], v[122:123], v[146:147] op_sel_hi:[1,0]
	v_exp_f32_e32 v148, v148
	v_exp_f32_e32 v149, v149
	v_exp_f32_e32 v122, v122
	v_exp_f32_e32 v123, v123
	v_mul_f32_e32 v144, v144, v144
	v_pk_add_f32 v[148:149], v[148:149], 1.0 op_sel_hi:[1,0]
	v_pk_mul_f32 v[120:121], v[124:125], v[120:121]
	v_pk_add_f32 v[122:123], v[122:123], 1.0 op_sel_hi:[1,0]
	v_rcp_f32_e32 v148, v148
	v_rcp_f32_e32 v149, v149
	v_rcp_f32_e32 v122, v122
	v_rcp_f32_e32 v123, v123
	v_pk_mul_f32 v[120:121], v[120:121], v[144:145] op_sel_hi:[1,0]
	v_pk_mul_f32 v[124:125], v[126:127], v[144:145] op_sel_hi:[1,0]
	v_pk_mul_f32 v[120:121], v[120:121], v[148:149]
	v_pk_mul_f32 v[122:123], v[124:125], v[122:123]
	v_cvt_pk_bf16_f32 v120, v120, v121
	v_cvt_pk_bf16_f32 v121, v122, v123
	v_pk_mul_f32 v[122:123], v[112:113], v[146:147] op_sel_hi:[1,0]
	v_pk_mul_f32 v[112:113], v[116:117], v[112:113]
	v_exp_f32_e32 v122, v122
	v_exp_f32_e32 v123, v123
	v_pk_mul_f32 v[112:113], v[112:113], v[144:145] op_sel_hi:[1,0]
	v_ashrrev_i32_e32 v143, 31, v142
	v_add_u32_e32 v116, s12, v132
	v_pk_add_f32 v[122:123], v[122:123], 1.0 op_sel_hi:[1,0]
	v_pk_mul_f32 v[110:111], v[110:111], v[106:107]
	v_rcp_f32_e32 v122, v122
	v_rcp_f32_e32 v123, v123
	v_pk_mul_f32 v[102:103], v[102:103], v[98:99]
	v_pk_mul_f32 v[94:95], v[94:95], v[90:91]
	v_pk_mul_f32 v[86:87], v[86:87], v[82:83]
	v_pk_mul_f32 v[112:113], v[112:113], v[122:123]
	v_pk_mul_f32 v[78:79], v[78:79], v[74:75]
	v_cvt_pk_bf16_f32 v122, v112, v113
	v_pk_mul_f32 v[112:113], v[114:115], v[146:147] op_sel_hi:[1,0]
	v_pk_mul_f32 v[114:115], v[118:119], v[144:145] op_sel_hi:[1,0]
	v_exp_f32_e32 v112, v112
	v_exp_f32_e32 v113, v113
	v_pk_mul_f32 v[70:71], v[70:71], v[66:67]
	v_pk_mul_f32 v[62:63], v[62:63], v[58:59]
	v_pk_mul_f32 v[54:55], v[54:55], v[50:51]
	v_pk_add_f32 v[112:113], v[112:113], 1.0 op_sel_hi:[1,0]
	v_pk_mul_f32 v[46:47], v[46:47], v[42:43]
	v_rcp_f32_e32 v112, v112
	v_rcp_f32_e32 v113, v113
	v_pk_mul_f32 v[38:39], v[38:39], v[34:35]
	v_pk_mul_f32 v[30:31], v[30:31], v[26:27]
	v_pk_mul_f32 v[22:23], v[22:23], v[18:19]
	v_pk_mul_f32 v[112:113], v[114:115], v[112:113]
	v_lshlrev_b64 v[114:115], 1, v[142:143]
	v_cvt_pk_bf16_f32 v123, v112, v113
	v_mov_b64_e32 v[112:113], s[16:17]
	v_mad_i64_i32 v[118:119], s[20:21], v116, s35, v[112:113]
	v_lshl_add_u64 v[118:119], v[118:119], 0, v[114:115]
	global_store_dwordx4 v[118:119], v[120:123], off
	v_mul_f32_e32 v118, 0xbfb8aa3b, v145
	v_pk_mul_f32 v[106:107], v[106:107], v[118:119] op_sel_hi:[1,0]
	v_pk_mul_f32 v[122:123], v[104:105], v[118:119] op_sel_hi:[1,0]
	v_exp_f32_e32 v106, v106
	v_exp_f32_e32 v122, v122
	v_exp_f32_e32 v123, v123
	v_exp_f32_e32 v107, v107
	v_mul_f32_e32 v120, v145, v145
	v_pk_mul_f32 v[104:105], v[108:109], v[104:105]
	v_pk_add_f32 v[122:123], v[122:123], 1.0 op_sel_hi:[1,0]
	v_pk_add_f32 v[106:107], v[106:107], 1.0 op_sel_hi:[1,0]
	v_rcp_f32_e32 v122, v122
	v_rcp_f32_e32 v123, v123
	v_rcp_f32_e32 v106, v106
	v_rcp_f32_e32 v107, v107
	v_pk_mul_f32 v[104:105], v[104:105], v[120:121] op_sel_hi:[1,0]
	v_pk_mul_f32 v[108:109], v[110:111], v[120:121] op_sel_hi:[1,0]
	v_pk_mul_f32 v[104:105], v[104:105], v[122:123]
	v_pk_mul_f32 v[106:107], v[108:109], v[106:107]
	v_cvt_pk_bf16_f32 v104, v104, v105
	v_cvt_pk_bf16_f32 v105, v106, v107
	v_pk_mul_f32 v[106:107], v[96:97], v[118:119] op_sel_hi:[1,0]
	v_pk_mul_f32 v[96:97], v[100:101], v[96:97]
	v_exp_f32_e32 v106, v106
	v_exp_f32_e32 v107, v107
	v_pk_mul_f32 v[96:97], v[96:97], v[120:121] op_sel_hi:[1,0]
	v_pk_mul_f32 v[14:15], v[14:15], v[10:11]
	v_pk_mul_f32 v[6:7], v[6:7], v[2:3]
	v_pk_add_f32 v[106:107], v[106:107], 1.0 op_sel_hi:[1,0]
	s_and_b64 vcc, exec, s[42:43]
	v_rcp_f32_e32 v106, v106
	v_rcp_f32_e32 v107, v107
	s_mov_b32 s79, s76
	s_mov_b32 s78, s77
	s_mov_b64 s[46:47], s[44:45]
	v_pk_mul_f32 v[96:97], v[96:97], v[106:107]
	s_mov_b64 s[52:53], s[0:1]
	v_cvt_pk_bf16_f32 v106, v96, v97
	v_pk_mul_f32 v[96:97], v[98:99], v[118:119] op_sel_hi:[1,0]
	v_pk_mul_f32 v[98:99], v[102:103], v[120:121] op_sel_hi:[1,0]
	v_exp_f32_e32 v96, v96
	v_exp_f32_e32 v97, v97
	s_nop 0
	v_pk_add_f32 v[96:97], v[96:97], 1.0 op_sel_hi:[1,0]
	s_nop 0
	v_rcp_f32_e32 v96, v96
	v_rcp_f32_e32 v97, v97
	s_nop 0
	v_pk_mul_f32 v[96:97], v[98:99], v[96:97]
	s_nop 0
	v_cvt_pk_bf16_f32 v107, v96, v97
	v_add_u32_e32 v96, s12, v134
	v_mad_i64_i32 v[96:97], s[20:21], v96, s35, v[112:113]
	v_lshl_add_u64 v[96:97], v[96:97], 0, v[114:115]
	global_store_dwordx4 v[96:97], v[104:107], off
	v_mov_b32_e32 v96, v174
	v_mov_b32_e32 v97, v175
	s_waitcnt lgkmcnt(0)
; __device__ __forceinline__ unsigned cvt_pk_bf16(float lo, float hi) { const f32x2 v = {lo, hi}; return __builtin_bit_cast(unsigned, __builtin_convertvector(v, bfx2_t)); }
;     __device__ __forceinline__ void operator()(const AccT& acc, const Unit& u, int ui, int wr, int wc, int fr, int fq) const {
;         const int col = u.pn * 128 + wc * 32 + 8 * fq;
; #pragma unroll
;         for (int ai = 0; ai < 2; ++ai)
; #pragma unroll
;             for (int m = 0; m < 4; ++m) {
;                 const int rl = ai * 128 + wr * 64 + m * 16 + fr; const float r = rs[((u.pm >> 3) & 3) * 256 + rl];
;                 const float nr = -1.4426950408889634f * r, r2 = r * r;
;                 unsigned w[4];
; #pragma unroll
;                 for (int n = 0; n < 2; ++n)
; #pragma unroll
;                     for (int hlf = 0; hlf < 2; ++hlf) {
;                         const f32x2 a = {acc[ai][0][m][n][2 * hlf], acc[ai][0][m][n][2 * hlf + 1]}, b = {acc[ai][1][m][n][2 * hlf], acc[ai][1][m][n][2 * hlf + 1]};
;                         const f32x2 t = a * nr;
;                         f32x2 d; d.x = __builtin_amdgcn_exp2f(t.x); d.y = __builtin_amdgcn_exp2f(t.y); d = d + 1.0f;
;                         f32x2 q; q.x = __builtin_amdgcn_rcpf(d.x); q.y = __builtin_amdgcn_rcpf(d.y);
;                         const f32x2 o = ((a * b) * r2) * q;
;                         w[n * 2 + hlf] = cvt_pk_bf16(o.x, o.y);
;                     }
;                 u32x4 wv; wv.x = w[0]; wv.y = w[1]; wv.z = w[2]; wv.w = w[3];
;                 *GP(u32x4, O + (size_t)(u.pm * 256 + rl) * FF + col) = wv;
	v_mul_f32_e32 v98, 0xbfb8aa3b, v96
	v_pk_mul_f32 v[100:101], v[88:89], v[98:99] op_sel_hi:[1,0]
	v_pk_mul_f32 v[90:91], v[90:91], v[98:99] op_sel_hi:[1,0]
	v_exp_f32_e32 v100, v100
	v_exp_f32_e32 v101, v101
	v_exp_f32_e32 v90, v90
	v_exp_f32_e32 v91, v91
	v_mul_f32_e32 v96, v96, v96
	v_pk_add_f32 v[100:101], v[100:101], 1.0 op_sel_hi:[1,0]
	v_pk_mul_f32 v[88:89], v[92:93], v[88:89]
	v_pk_add_f32 v[90:91], v[90:91], 1.0 op_sel_hi:[1,0]
	v_rcp_f32_e32 v100, v100
	v_rcp_f32_e32 v101, v101
	v_rcp_f32_e32 v90, v90
	v_rcp_f32_e32 v91, v91
	v_pk_mul_f32 v[88:89], v[88:89], v[96:97] op_sel_hi:[1,0]
	v_pk_mul_f32 v[92:93], v[94:95], v[96:97] op_sel_hi:[1,0]
	v_pk_mul_f32 v[88:89], v[88:89], v[100:101]
	v_pk_mul_f32 v[90:91], v[92:93], v[90:91]
	v_cvt_pk_bf16_f32 v88, v88, v89
	v_cvt_pk_bf16_f32 v89, v90, v91
	v_pk_mul_f32 v[90:91], v[80:81], v[98:99] op_sel_hi:[1,0]
	v_pk_mul_f32 v[80:81], v[84:85], v[80:81]
	v_exp_f32_e32 v90, v90
	v_exp_f32_e32 v91, v91
	v_pk_mul_f32 v[80:81], v[80:81], v[96:97] op_sel_hi:[1,0]
	v_pk_add_f32 v[90:91], v[90:91], 1.0 op_sel_hi:[1,0]
	s_nop 0
	v_rcp_f32_e32 v90, v90
	v_rcp_f32_e32 v91, v91
	s_nop 0
	v_pk_mul_f32 v[80:81], v[80:81], v[90:91]
	s_nop 0
	v_cvt_pk_bf16_f32 v90, v80, v81
	v_pk_mul_f32 v[80:81], v[82:83], v[98:99] op_sel_hi:[1,0]
	v_pk_mul_f32 v[82:83], v[86:87], v[96:97] op_sel_hi:[1,0]
	v_exp_f32_e32 v80, v80
	v_exp_f32_e32 v81, v81
	s_nop 0
	v_pk_add_f32 v[80:81], v[80:81], 1.0 op_sel_hi:[1,0]
	s_nop 0
	v_rcp_f32_e32 v80, v80
	v_rcp_f32_e32 v81, v81
	s_nop 0
	v_pk_mul_f32 v[80:81], v[82:83], v[80:81]
	s_nop 0
	v_cvt_pk_bf16_f32 v91, v80, v81
	v_add_u32_e32 v80, s12, v135
	v_mad_i64_i32 v[80:81], s[20:21], v80, s35, v[112:113]
	v_lshl_add_u64 v[80:81], v[80:81], 0, v[114:115]
	global_store_dwordx4 v[80:81], v[88:91], off
	v_mul_f32_e32 v80, 0xbfb8aa3b, v97
	v_pk_mul_f32 v[84:85], v[72:73], v[80:81] op_sel_hi:[1,0]
	v_pk_mul_f32 v[74:75], v[74:75], v[80:81] op_sel_hi:[1,0]
	v_exp_f32_e32 v84, v84
	v_exp_f32_e32 v85, v85
	v_exp_f32_e32 v74, v74
	v_exp_f32_e32 v75, v75
	v_mul_f32_e32 v82, v97, v97
	v_pk_add_f32 v[84:85], v[84:85], 1.0 op_sel_hi:[1,0]
	v_pk_mul_f32 v[72:73], v[76:77], v[72:73]
	v_pk_add_f32 v[74:75], v[74:75], 1.0 op_sel_hi:[1,0]
	v_rcp_f32_e32 v84, v84
	v_rcp_f32_e32 v85, v85
	v_rcp_f32_e32 v74, v74
	v_rcp_f32_e32 v75, v75
	v_pk_mul_f32 v[72:73], v[72:73], v[82:83] op_sel_hi:[1,0]
	v_pk_mul_f32 v[76:77], v[78:79], v[82:83] op_sel_hi:[1,0]
	v_pk_mul_f32 v[72:73], v[72:73], v[84:85]
	v_pk_mul_f32 v[74:75], v[76:77], v[74:75]
	v_cvt_pk_bf16_f32 v72, v72, v73
	v_cvt_pk_bf16_f32 v73, v74, v75
	v_pk_mul_f32 v[74:75], v[64:65], v[80:81] op_sel_hi:[1,0]
	v_pk_mul_f32 v[64:65], v[68:69], v[64:65]
	v_exp_f32_e32 v74, v74
	v_exp_f32_e32 v75, v75
	v_pk_mul_f32 v[64:65], v[64:65], v[82:83] op_sel_hi:[1,0]
	v_pk_add_f32 v[74:75], v[74:75], 1.0 op_sel_hi:[1,0]
	s_nop 0
	v_rcp_f32_e32 v74, v74
	v_rcp_f32_e32 v75, v75
	s_nop 0
	v_pk_mul_f32 v[64:65], v[64:65], v[74:75]
	s_nop 0
	v_cvt_pk_bf16_f32 v74, v64, v65
	v_pk_mul_f32 v[64:65], v[66:67], v[80:81] op_sel_hi:[1,0]
	v_pk_mul_f32 v[66:67], v[70:71], v[82:83] op_sel_hi:[1,0]
	v_exp_f32_e32 v64, v64
	v_exp_f32_e32 v65, v65
	s_nop 0
	v_pk_add_f32 v[64:65], v[64:65], 1.0 op_sel_hi:[1,0]
	s_nop 0
	v_rcp_f32_e32 v64, v64
	v_rcp_f32_e32 v65, v65
	s_nop 0
	v_pk_mul_f32 v[64:65], v[66:67], v[64:65]
	s_nop 0
	v_cvt_pk_bf16_f32 v75, v64, v65
	v_add_u32_e32 v64, s12, v136
	v_mad_i64_i32 v[64:65], s[12:13], v64, s35, v[112:113]
	v_lshl_add_u64 v[64:65], v[64:65], 0, v[114:115]
	global_store_dwordx4 v[64:65], v[72:75], off
	v_mov_b32_e32 v64, v176
	v_mov_b32_e32 v65, v177
	s_waitcnt lgkmcnt(0)
	v_mul_f32_e32 v66, 0xbfb8aa3b, v64
	v_pk_mul_f32 v[68:69], v[56:57], v[66:67] op_sel_hi:[1,0]
	v_pk_mul_f32 v[58:59], v[58:59], v[66:67] op_sel_hi:[1,0]
	v_exp_f32_e32 v68, v68
	v_exp_f32_e32 v69, v69
	v_exp_f32_e32 v58, v58
	v_exp_f32_e32 v59, v59
	v_mul_f32_e32 v64, v64, v64
	v_pk_add_f32 v[68:69], v[68:69], 1.0 op_sel_hi:[1,0]
	v_pk_mul_f32 v[56:57], v[60:61], v[56:57]
	v_pk_add_f32 v[58:59], v[58:59], 1.0 op_sel_hi:[1,0]
	v_rcp_f32_e32 v68, v68
	v_rcp_f32_e32 v69, v69
	v_rcp_f32_e32 v58, v58
	v_rcp_f32_e32 v59, v59
	v_pk_mul_f32 v[56:57], v[56:57], v[64:65] op_sel_hi:[1,0]
	v_pk_mul_f32 v[60:61], v[62:63], v[64:65] op_sel_hi:[1,0]
	v_pk_mul_f32 v[56:57], v[56:57], v[68:69]
	v_pk_mul_f32 v[58:59], v[60:61], v[58:59]
	v_cvt_pk_bf16_f32 v56, v56, v57
	v_cvt_pk_bf16_f32 v57, v58, v59
	v_pk_mul_f32 v[58:59], v[48:49], v[66:67] op_sel_hi:[1,0]
	v_pk_mul_f32 v[48:49], v[52:53], v[48:49]
	v_exp_f32_e32 v58, v58
	v_exp_f32_e32 v59, v59
	v_pk_mul_f32 v[48:49], v[48:49], v[64:65] op_sel_hi:[1,0]
	v_pk_add_f32 v[58:59], v[58:59], 1.0 op_sel_hi:[1,0]
	s_nop 0
	v_rcp_f32_e32 v58, v58
	v_rcp_f32_e32 v59, v59
	s_nop 0
	v_pk_mul_f32 v[48:49], v[48:49], v[58:59]
	s_nop 0
	v_cvt_pk_bf16_f32 v58, v48, v49
	v_pk_mul_f32 v[48:49], v[50:51], v[66:67] op_sel_hi:[1,0]
	v_pk_mul_f32 v[50:51], v[54:55], v[64:65] op_sel_hi:[1,0]
	v_exp_f32_e32 v48, v48
	v_exp_f32_e32 v49, v49
	s_nop 0
	v_pk_add_f32 v[48:49], v[48:49], 1.0 op_sel_hi:[1,0]
	s_nop 0
	v_rcp_f32_e32 v48, v48
	v_rcp_f32_e32 v49, v49
	s_nop 0
	v_pk_mul_f32 v[48:49], v[50:51], v[48:49]
	s_nop 0
	v_cvt_pk_bf16_f32 v59, v48, v49
	v_add_u32_e32 v48, 0x80, v116
	v_mad_i64_i32 v[48:49], s[12:13], v48, s35, v[112:113]
	v_lshl_add_u64 v[48:49], v[48:49], 0, v[114:115]
; __device__ __forceinline__ unsigned cvt_pk_bf16(float lo, float hi) { const f32x2 v = {lo, hi}; return __builtin_bit_cast(unsigned, __builtin_convertvector(v, bfx2_t)); }
;     __device__ __forceinline__ void operator()(const AccT& acc, const Unit& u, int ui, int wr, int wc, int fr, int fq) const {
;         const int col = u.pn * 128 + wc * 32 + 8 * fq;
; #pragma unroll
;         for (int ai = 0; ai < 2; ++ai)
; #pragma unroll
;             for (int m = 0; m < 4; ++m) {
;                 const int rl = ai * 128 + wr * 64 + m * 16 + fr; const float r = rs[((u.pm >> 3) & 3) * 256 + rl];
;                 const float nr = -1.4426950408889634f * r, r2 = r * r;
;                 unsigned w[4];
; #pragma unroll
;                 for (int n = 0; n < 2; ++n)
; #pragma unroll
;                     for (int hlf = 0; hlf < 2; ++hlf) {
;                         const f32x2 a = {acc[ai][0][m][n][2 * hlf], acc[ai][0][m][n][2 * hlf + 1]}, b = {acc[ai][1][m][n][2 * hlf], acc[ai][1][m][n][2 * hlf + 1]};
;                         const f32x2 t = a * nr;
;                         f32x2 d; d.x = __builtin_amdgcn_exp2f(t.x); d.y = __builtin_amdgcn_exp2f(t.y); d = d + 1.0f;
;                         f32x2 q; q.x = __builtin_amdgcn_rcpf(d.x); q.y = __builtin_amdgcn_rcpf(d.y);
;                         const f32x2 o = ((a * b) * r2) * q;
;                         w[n * 2 + hlf] = cvt_pk_bf16(o.x, o.y);
;                     }
;                 u32x4 wv; wv.x = w[0]; wv.y = w[1]; wv.z = w[2]; wv.w = w[3];
;                 *GP(u32x4, O + (size_t)(u.pm * 256 + rl) * FF + col) = wv;
	global_store_dwordx4 v[48:49], v[56:59], off
	v_mul_f32_e32 v48, 0xbfb8aa3b, v65
	v_pk_mul_f32 v[52:53], v[40:41], v[48:49] op_sel_hi:[1,0]
	v_pk_mul_f32 v[42:43], v[42:43], v[48:49] op_sel_hi:[1,0]
	v_exp_f32_e32 v52, v52
	v_exp_f32_e32 v53, v53
	v_exp_f32_e32 v42, v42
	v_exp_f32_e32 v43, v43
	v_mul_f32_e32 v50, v65, v65
	v_pk_add_f32 v[52:53], v[52:53], 1.0 op_sel_hi:[1,0]
	v_pk_mul_f32 v[40:41], v[44:45], v[40:41]
	v_pk_add_f32 v[42:43], v[42:43], 1.0 op_sel_hi:[1,0]
	v_rcp_f32_e32 v52, v52
	v_rcp_f32_e32 v53, v53
	v_rcp_f32_e32 v42, v42
	v_rcp_f32_e32 v43, v43
	v_pk_mul_f32 v[40:41], v[40:41], v[50:51] op_sel_hi:[1,0]
	v_pk_mul_f32 v[44:45], v[46:47], v[50:51] op_sel_hi:[1,0]
	v_pk_mul_f32 v[40:41], v[40:41], v[52:53]
	v_pk_mul_f32 v[42:43], v[44:45], v[42:43]
	v_cvt_pk_bf16_f32 v40, v40, v41
	v_cvt_pk_bf16_f32 v41, v42, v43
	v_pk_mul_f32 v[42:43], v[32:33], v[48:49] op_sel_hi:[1,0]
	v_pk_mul_f32 v[32:33], v[36:37], v[32:33]
	v_exp_f32_e32 v42, v42
	v_exp_f32_e32 v43, v43
	v_pk_mul_f32 v[32:33], v[32:33], v[50:51] op_sel_hi:[1,0]
	v_pk_add_f32 v[42:43], v[42:43], 1.0 op_sel_hi:[1,0]
	s_nop 0
	v_rcp_f32_e32 v42, v42
	v_rcp_f32_e32 v43, v43
	s_nop 0
	v_pk_mul_f32 v[32:33], v[32:33], v[42:43]
	s_nop 0
	v_cvt_pk_bf16_f32 v42, v32, v33
	v_pk_mul_f32 v[32:33], v[34:35], v[48:49] op_sel_hi:[1,0]
	v_pk_mul_f32 v[34:35], v[38:39], v[50:51] op_sel_hi:[1,0]
	v_exp_f32_e32 v32, v32
	v_exp_f32_e32 v33, v33
	s_nop 0
	v_pk_add_f32 v[32:33], v[32:33], 1.0 op_sel_hi:[1,0]
	s_nop 0
	v_rcp_f32_e32 v32, v32
	v_rcp_f32_e32 v33, v33
	s_nop 0
	v_pk_mul_f32 v[32:33], v[34:35], v[32:33]
	s_nop 0
	v_cvt_pk_bf16_f32 v43, v32, v33
	v_add_u32_e32 v32, 0x90, v116
	v_mad_i64_i32 v[32:33], s[12:13], v32, s35, v[112:113]
	v_lshl_add_u64 v[32:33], v[32:33], 0, v[114:115]
	global_store_dwordx4 v[32:33], v[40:43], off
	v_mov_b32_e32 v32, v178
	v_mov_b32_e32 v33, v179
	s_waitcnt lgkmcnt(0)
	v_mul_f32_e32 v34, 0xbfb8aa3b, v32
	v_pk_mul_f32 v[36:37], v[24:25], v[34:35] op_sel_hi:[1,0]
	v_pk_mul_f32 v[26:27], v[26:27], v[34:35] op_sel_hi:[1,0]
	v_exp_f32_e32 v36, v36
	v_exp_f32_e32 v37, v37
	v_exp_f32_e32 v26, v26
	v_exp_f32_e32 v27, v27
	v_mul_f32_e32 v32, v32, v32
	v_pk_add_f32 v[36:37], v[36:37], 1.0 op_sel_hi:[1,0]
	v_pk_mul_f32 v[24:25], v[28:29], v[24:25]
	v_pk_add_f32 v[26:27], v[26:27], 1.0 op_sel_hi:[1,0]
	v_rcp_f32_e32 v36, v36
	v_rcp_f32_e32 v37, v37
	v_rcp_f32_e32 v26, v26
	v_rcp_f32_e32 v27, v27
	v_pk_mul_f32 v[24:25], v[24:25], v[32:33] op_sel_hi:[1,0]
	v_pk_mul_f32 v[28:29], v[30:31], v[32:33] op_sel_hi:[1,0]
	v_pk_mul_f32 v[24:25], v[24:25], v[36:37]
	v_pk_mul_f32 v[26:27], v[28:29], v[26:27]
	v_cvt_pk_bf16_f32 v24, v24, v25
	v_cvt_pk_bf16_f32 v25, v26, v27
	v_pk_mul_f32 v[26:27], v[16:17], v[34:35] op_sel_hi:[1,0]
	v_pk_mul_f32 v[16:17], v[20:21], v[16:17]
	v_exp_f32_e32 v26, v26
	v_exp_f32_e32 v27, v27
	v_pk_mul_f32 v[16:17], v[16:17], v[32:33] op_sel_hi:[1,0]
	v_pk_add_f32 v[26:27], v[26:27], 1.0 op_sel_hi:[1,0]
	s_nop 0
	v_rcp_f32_e32 v26, v26
	v_rcp_f32_e32 v27, v27
	s_nop 0
	v_pk_mul_f32 v[16:17], v[16:17], v[26:27]
	s_nop 0
	v_cvt_pk_bf16_f32 v26, v16, v17
	v_pk_mul_f32 v[16:17], v[18:19], v[34:35] op_sel_hi:[1,0]
	v_pk_mul_f32 v[18:19], v[22:23], v[32:33] op_sel_hi:[1,0]
	v_exp_f32_e32 v16, v16
	v_exp_f32_e32 v17, v17
	s_nop 0
	v_pk_add_f32 v[16:17], v[16:17], 1.0 op_sel_hi:[1,0]
	s_nop 0
	v_rcp_f32_e32 v16, v16
	v_rcp_f32_e32 v17, v17
	s_nop 0
	v_pk_mul_f32 v[16:17], v[18:19], v[16:17]
	s_nop 0
	v_cvt_pk_bf16_f32 v27, v16, v17
	v_add_u32_e32 v16, 0xa0, v116
	v_mad_i64_i32 v[16:17], s[12:13], v16, s35, v[112:113]
	v_lshl_add_u64 v[16:17], v[16:17], 0, v[114:115]
	global_store_dwordx4 v[16:17], v[24:27], off
	v_mul_f32_e32 v16, 0xbfb8aa3b, v33
	v_pk_mul_f32 v[20:21], v[8:9], v[16:17] op_sel_hi:[1,0]
	v_pk_mul_f32 v[10:11], v[10:11], v[16:17] op_sel_hi:[1,0]
	v_exp_f32_e32 v20, v20
	v_exp_f32_e32 v21, v21
	v_exp_f32_e32 v10, v10
	v_exp_f32_e32 v11, v11
	v_mul_f32_e32 v18, v33, v33
	v_pk_add_f32 v[20:21], v[20:21], 1.0 op_sel_hi:[1,0]
	v_pk_mul_f32 v[8:9], v[12:13], v[8:9]
	v_pk_add_f32 v[10:11], v[10:11], 1.0 op_sel_hi:[1,0]
	v_rcp_f32_e32 v20, v20
	v_rcp_f32_e32 v21, v21
	v_rcp_f32_e32 v10, v10
	v_rcp_f32_e32 v11, v11
	v_pk_mul_f32 v[8:9], v[8:9], v[18:19] op_sel_hi:[1,0]
	v_pk_mul_f32 v[12:13], v[14:15], v[18:19] op_sel_hi:[1,0]
	v_pk_mul_f32 v[8:9], v[8:9], v[20:21]
	v_pk_mul_f32 v[10:11], v[12:13], v[10:11]
	v_cvt_pk_bf16_f32 v8, v8, v9
	v_cvt_pk_bf16_f32 v9, v10, v11
	v_pk_mul_f32 v[10:11], v[0:1], v[16:17] op_sel_hi:[1,0]
	v_pk_mul_f32 v[0:1], v[4:5], v[0:1]
	v_exp_f32_e32 v10, v10
	v_exp_f32_e32 v11, v11
	v_pk_mul_f32 v[0:1], v[0:1], v[18:19] op_sel_hi:[1,0]
	v_pk_add_f32 v[10:11], v[10:11], 1.0 op_sel_hi:[1,0]
	s_nop 0
	v_rcp_f32_e32 v10, v10
	v_rcp_f32_e32 v11, v11
	s_nop 0
	v_pk_mul_f32 v[0:1], v[0:1], v[10:11]
	s_nop 0
	v_cvt_pk_bf16_f32 v10, v0, v1
	v_pk_mul_f32 v[0:1], v[2:3], v[16:17] op_sel_hi:[1,0]
	v_pk_mul_f32 v[2:3], v[6:7], v[18:19] op_sel_hi:[1,0]
	v_exp_f32_e32 v0, v0
	v_exp_f32_e32 v1, v1
	s_nop 0
	v_pk_add_f32 v[0:1], v[0:1], 1.0 op_sel_hi:[1,0]
	s_nop 0
	v_rcp_f32_e32 v0, v0
	v_rcp_f32_e32 v1, v1
	s_nop 0
	v_pk_mul_f32 v[0:1], v[2:3], v[0:1]
	s_nop 0
	v_cvt_pk_bf16_f32 v11, v0, v1
	v_add_u32_e32 v0, 0xb0, v116
	v_mad_i64_i32 v[0:1], s[12:13], v0, s35, v[112:113]
	v_lshl_add_u64 v[0:1], v[0:1], 0, v[114:115]
	global_store_dwordx4 v[0:1], v[8:11], off
	s_cbranch_vccnz .LBB0_237

; template <class Epi, class Ord>
; __device__ __forceinline__ void gemm_phase(LAS unsigned char* lds, const Gemm g, const Ord& S, const Epi& E) {
;     ...
; #pragma unroll
;         for (int a = 0; a < 2; ++a)
; #pragma unroll
;             for (int b = 0; b < 2; ++b)
; #pragma unroll
;                 for (int m = 0; m < 4; ++m)
; #pragma unroll
;                     for (int n = 0; n < 2; ++n) acc[a][b][m][n] = (f32x4){0.f, 0.f, 0.f, 0.f};
.LBB0_234:
	v_mov_b32_e32 v123, 0
	v_mov_b32_e32 v122, 0
	s_andn2_b64 vcc, exec, s[18:19]
	v_pk_mov_b32 v[120:121], v[122:123], v[122:123]
	v_pk_mov_b32 v[114:115], v[122:123], v[122:123]
	v_pk_mov_b32 v[112:113], v[122:123], v[122:123]
	v_pk_mov_b32 v[106:107], v[122:123], v[122:123]
	v_pk_mov_b32 v[104:105], v[122:123], v[122:123]
	v_pk_mov_b32 v[98:99], v[122:123], v[122:123]
	v_pk_mov_b32 v[96:97], v[122:123], v[122:123]
	v_pk_mov_b32 v[90:91], v[122:123], v[122:123]
	v_pk_mov_b32 v[88:89], v[122:123], v[122:123]
	v_pk_mov_b32 v[82:83], v[122:123], v[122:123]
	v_pk_mov_b32 v[80:81], v[122:123], v[122:123]
	v_pk_mov_b32 v[74:75], v[122:123], v[122:123]
	v_pk_mov_b32 v[72:73], v[122:123], v[122:123]
	v_pk_mov_b32 v[66:67], v[122:123], v[122:123]
	v_pk_mov_b32 v[64:65], v[122:123], v[122:123]
	v_pk_mov_b32 v[126:127], v[122:123], v[122:123]
	v_pk_mov_b32 v[124:125], v[122:123], v[122:123]
	v_pk_mov_b32 v[118:119], v[122:123], v[122:123]
	v_pk_mov_b32 v[116:117], v[122:123], v[122:123]
	v_pk_mov_b32 v[110:111], v[122:123], v[122:123]
	v_pk_mov_b32 v[108:109], v[122:123], v[122:123]
	v_pk_mov_b32 v[102:103], v[122:123], v[122:123]
	v_pk_mov_b32 v[100:101], v[122:123], v[122:123]
	v_pk_mov_b32 v[94:95], v[122:123], v[122:123]
	v_pk_mov_b32 v[92:93], v[122:123], v[122:123]
	v_pk_mov_b32 v[86:87], v[122:123], v[122:123]
	v_pk_mov_b32 v[84:85], v[122:123], v[122:123]
	v_pk_mov_b32 v[78:79], v[122:123], v[122:123]
	v_pk_mov_b32 v[76:77], v[122:123], v[122:123]
	v_pk_mov_b32 v[70:71], v[122:123], v[122:123]
	v_pk_mov_b32 v[68:69], v[122:123], v[122:123]
	v_pk_mov_b32 v[58:59], v[122:123], v[122:123]
	v_pk_mov_b32 v[56:57], v[122:123], v[122:123]
	v_pk_mov_b32 v[50:51], v[122:123], v[122:123]
	v_pk_mov_b32 v[48:49], v[122:123], v[122:123]
	v_pk_mov_b32 v[42:43], v[122:123], v[122:123]
	v_pk_mov_b32 v[40:41], v[122:123], v[122:123]
	v_pk_mov_b32 v[34:35], v[122:123], v[122:123]
	v_pk_mov_b32 v[32:33], v[122:123], v[122:123]
	v_pk_mov_b32 v[26:27], v[122:123], v[122:123]
	v_pk_mov_b32 v[24:25], v[122:123], v[122:123]
	v_pk_mov_b32 v[18:19], v[122:123], v[122:123]
	v_pk_mov_b32 v[16:17], v[122:123], v[122:123]
	v_pk_mov_b32 v[10:11], v[122:123], v[122:123]
	v_pk_mov_b32 v[8:9], v[122:123], v[122:123]
	v_pk_mov_b32 v[2:3], v[122:123], v[122:123]
	v_pk_mov_b32 v[0:1], v[122:123], v[122:123]
	v_pk_mov_b32 v[62:63], v[122:123], v[122:123]
	v_pk_mov_b32 v[60:61], v[122:123], v[122:123]
	v_pk_mov_b32 v[54:55], v[122:123], v[122:123]
	v_pk_mov_b32 v[52:53], v[122:123], v[122:123]
	v_pk_mov_b32 v[46:47], v[122:123], v[122:123]
	v_pk_mov_b32 v[44:45], v[122:123], v[122:123]
	v_pk_mov_b32 v[38:39], v[122:123], v[122:123]
	v_pk_mov_b32 v[36:37], v[122:123], v[122:123]
	v_pk_mov_b32 v[30:31], v[122:123], v[122:123]
	v_pk_mov_b32 v[28:29], v[122:123], v[122:123]
	v_pk_mov_b32 v[22:23], v[122:123], v[122:123]
	v_pk_mov_b32 v[20:21], v[122:123], v[122:123]
	v_pk_mov_b32 v[14:15], v[122:123], v[122:123]
	v_pk_mov_b32 v[12:13], v[122:123], v[122:123]
	v_pk_mov_b32 v[6:7], v[122:123], v[122:123]
	v_pk_mov_b32 v[4:5], v[122:123], v[122:123]
	s_cbranch_vccnz .LBB0_227
	s_add_u32 s46, s46, 0x100
	s_addc_u32 s47, s47, 0
	s_add_u32 s52, s52, 0x100
	v_mov_b32_e32 v4, 0
	v_mov_b32_e32 v5, 0
	s_addc_u32 s53, s53, 0
	s_mov_b32 s12, 0
	v_pk_mov_b32 v[6:7], v[4:5], v[4:5]
	v_pk_mov_b32 v[12:13], v[4:5], v[4:5]
	v_pk_mov_b32 v[14:15], v[4:5], v[4:5]
	v_pk_mov_b32 v[20:21], v[4:5], v[4:5]
	v_pk_mov_b32 v[22:23], v[4:5], v[4:5]
	v_pk_mov_b32 v[28:29], v[4:5], v[4:5]
	v_pk_mov_b32 v[30:31], v[4:5], v[4:5]
	v_pk_mov_b32 v[36:37], v[4:5], v[4:5]
	v_pk_mov_b32 v[38:39], v[4:5], v[4:5]
	v_pk_mov_b32 v[44:45], v[4:5], v[4:5]
	v_pk_mov_b32 v[46:47], v[4:5], v[4:5]
	v_pk_mov_b32 v[52:53], v[4:5], v[4:5]
	v_pk_mov_b32 v[54:55], v[4:5], v[4:5]
	v_pk_mov_b32 v[60:61], v[4:5], v[4:5]
	v_pk_mov_b32 v[62:63], v[4:5], v[4:5]
	v_pk_mov_b32 v[0:1], v[4:5], v[4:5]
	v_pk_mov_b32 v[2:3], v[4:5], v[4:5]
	v_pk_mov_b32 v[8:9], v[4:5], v[4:5]
	v_pk_mov_b32 v[10:11], v[4:5], v[4:5]
	v_pk_mov_b32 v[16:17], v[4:5], v[4:5]
	v_pk_mov_b32 v[18:19], v[4:5], v[4:5]
	v_pk_mov_b32 v[24:25], v[4:5], v[4:5]
	v_pk_mov_b32 v[26:27], v[4:5], v[4:5]
	v_pk_mov_b32 v[32:33], v[4:5], v[4:5]
	v_pk_mov_b32 v[34:35], v[4:5], v[4:5]
	v_pk_mov_b32 v[40:41], v[4:5], v[4:5]
	v_pk_mov_b32 v[42:43], v[4:5], v[4:5]
	v_pk_mov_b32 v[48:49], v[4:5], v[4:5]
	v_pk_mov_b32 v[50:51], v[4:5], v[4:5]
	v_pk_mov_b32 v[56:57], v[4:5], v[4:5]
	v_pk_mov_b32 v[58:59], v[4:5], v[4:5]
	v_pk_mov_b32 v[68:69], v[4:5], v[4:5]
	v_pk_mov_b32 v[70:71], v[4:5], v[4:5]
	v_pk_mov_b32 v[76:77], v[4:5], v[4:5]
	v_pk_mov_b32 v[78:79], v[4:5], v[4:5]
	v_pk_mov_b32 v[84:85], v[4:5], v[4:5]
	v_pk_mov_b32 v[86:87], v[4:5], v[4:5]
	v_pk_mov_b32 v[92:93], v[4:5], v[4:5]
	v_pk_mov_b32 v[94:95], v[4:5], v[4:5]
	v_pk_mov_b32 v[100:101], v[4:5], v[4:5]
	v_pk_mov_b32 v[102:103], v[4:5], v[4:5]
	v_pk_mov_b32 v[108:109], v[4:5], v[4:5]
	v_pk_mov_b32 v[110:111], v[4:5], v[4:5]
	v_pk_mov_b32 v[116:117], v[4:5], v[4:5]
	v_pk_mov_b32 v[118:119], v[4:5], v[4:5]
	v_pk_mov_b32 v[124:125], v[4:5], v[4:5]
	v_pk_mov_b32 v[126:127], v[4:5], v[4:5]
	v_pk_mov_b32 v[64:65], v[4:5], v[4:5]
	v_pk_mov_b32 v[66:67], v[4:5], v[4:5]
	v_pk_mov_b32 v[72:73], v[4:5], v[4:5]
	v_pk_mov_b32 v[74:75], v[4:5], v[4:5]
	v_pk_mov_b32 v[80:81], v[4:5], v[4:5]
	v_pk_mov_b32 v[82:83], v[4:5], v[4:5]
	v_pk_mov_b32 v[88:89], v[4:5], v[4:5]
	v_pk_mov_b32 v[90:91], v[4:5], v[4:5]
	v_pk_mov_b32 v[96:97], v[4:5], v[4:5]
	v_pk_mov_b32 v[98:99], v[4:5], v[4:5]
	v_pk_mov_b32 v[104:105], v[4:5], v[4:5]
	v_pk_mov_b32 v[106:107], v[4:5], v[4:5]
	v_pk_mov_b32 v[112:113], v[4:5], v[4:5]
	v_pk_mov_b32 v[114:115], v[4:5], v[4:5]
	v_pk_mov_b32 v[120:121], v[4:5], v[4:5]
	v_pk_mov_b32 v[122:123], v[4:5], v[4:5]

; template <class Epi, class Ord>
; __device__ __forceinline__ void gemm_phase(LAS unsigned char* lds, const Gemm g, const Ord& S, const Epi& E) {
;     ...
; #pragma unroll
;         for (int a = 0; a < 2; ++a)
; #pragma unroll
;             for (int b = 0; b < 2; ++b)
; #pragma unroll
;                 for (int m = 0; m < 4; ++m)
; #pragma unroll
;                     for (int n = 0; n < 2; ++n) acc[a][b][m][n] = (f32x4){0.f, 0.f, 0.f, 0.f};
;         cur = nxt; cA = nA; cB = nB; ++ui;
.LBB0_267:
	v_mov_b32_e32 v127, 0
	s_andn2_b64 vcc, exec, s[16:17]
	v_mov_b32_e32 v126, v127
	v_mov_b32_e32 v125, v127
	v_mov_b32_e32 v124, v127
	v_mov_b32_e32 v123, v127
	v_mov_b32_e32 v122, v127
	v_mov_b32_e32 v121, v127
	v_mov_b32_e32 v120, v127
	v_mov_b32_e32 v111, v127
	v_mov_b32_e32 v110, v127
	v_mov_b32_e32 v109, v127
	v_mov_b32_e32 v108, v127
	v_mov_b32_e32 v107, v127
	v_mov_b32_e32 v106, v127
	v_mov_b32_e32 v105, v127
	v_mov_b32_e32 v104, v127
	v_mov_b32_e32 v95, v127
	v_mov_b32_e32 v94, v127
	v_mov_b32_e32 v93, v127
	v_mov_b32_e32 v92, v127
	v_mov_b32_e32 v91, v127
	v_mov_b32_e32 v90, v127
	v_mov_b32_e32 v89, v127
	v_mov_b32_e32 v88, v127
	v_mov_b32_e32 v79, v127
	v_mov_b32_e32 v78, v127
	v_mov_b32_e32 v77, v127
	v_mov_b32_e32 v76, v127
	v_mov_b32_e32 v75, v127
	v_mov_b32_e32 v74, v127
	v_mov_b32_e32 v73, v127
	v_mov_b32_e32 v72, v127
	v_mov_b32_e32 v119, v127
	v_mov_b32_e32 v118, v127
	v_mov_b32_e32 v117, v127
	v_mov_b32_e32 v116, v127
	v_mov_b32_e32 v115, v127
	v_mov_b32_e32 v114, v127
	v_mov_b32_e32 v113, v127
	v_mov_b32_e32 v112, v127
	v_mov_b32_e32 v103, v127
	v_mov_b32_e32 v102, v127
	v_mov_b32_e32 v101, v127
	v_mov_b32_e32 v100, v127
	v_mov_b32_e32 v99, v127
	v_mov_b32_e32 v98, v127
	v_mov_b32_e32 v97, v127
	v_mov_b32_e32 v96, v127
	v_mov_b32_e32 v87, v127
	v_mov_b32_e32 v86, v127
	v_mov_b32_e32 v85, v127
	v_mov_b32_e32 v84, v127
	v_mov_b32_e32 v83, v127
	v_mov_b32_e32 v82, v127
	v_mov_b32_e32 v81, v127
	v_mov_b32_e32 v80, v127
	v_mov_b32_e32 v71, v127
	v_mov_b32_e32 v70, v127
	v_mov_b32_e32 v69, v127
	v_mov_b32_e32 v68, v127
	v_mov_b32_e32 v67, v127
	v_mov_b32_e32 v66, v127
	v_mov_b32_e32 v65, v127
	v_mov_b32_e32 v64, v127
	v_mov_b32_e32 v63, v127
	v_mov_b32_e32 v62, v127
	v_mov_b32_e32 v61, v127
	v_mov_b32_e32 v60, v127
	v_mov_b32_e32 v59, v127
	v_mov_b32_e32 v58, v127
	v_mov_b32_e32 v57, v127
	v_mov_b32_e32 v56, v127
	v_mov_b32_e32 v47, v127
	v_mov_b32_e32 v46, v127
	v_mov_b32_e32 v45, v127
	v_mov_b32_e32 v44, v127
	v_mov_b32_e32 v43, v127
	v_mov_b32_e32 v42, v127
	v_mov_b32_e32 v41, v127
	v_mov_b32_e32 v40, v127
	v_mov_b32_e32 v31, v127
	v_mov_b32_e32 v30, v127
	v_mov_b32_e32 v29, v127
	v_mov_b32_e32 v28, v127
	v_mov_b32_e32 v27, v127
	v_mov_b32_e32 v26, v127
	v_mov_b32_e32 v25, v127
	v_mov_b32_e32 v24, v127
	v_mov_b32_e32 v15, v127
	v_mov_b32_e32 v14, v127
	v_mov_b32_e32 v13, v127
	v_mov_b32_e32 v12, v127
	v_mov_b32_e32 v11, v127
	v_mov_b32_e32 v10, v127
	v_mov_b32_e32 v9, v127
	v_mov_b32_e32 v8, v127
	v_mov_b32_e32 v55, v127
	v_mov_b32_e32 v54, v127
	v_mov_b32_e32 v53, v127
	v_mov_b32_e32 v52, v127
	v_mov_b32_e32 v51, v127
	v_mov_b32_e32 v50, v127
	v_mov_b32_e32 v49, v127
	v_mov_b32_e32 v48, v127
	v_mov_b32_e32 v39, v127
	v_mov_b32_e32 v38, v127
	v_mov_b32_e32 v37, v127
	v_mov_b32_e32 v36, v127
	v_mov_b32_e32 v35, v127
	v_mov_b32_e32 v34, v127
	v_mov_b32_e32 v33, v127
	v_mov_b32_e32 v32, v127
	v_mov_b32_e32 v23, v127
	v_mov_b32_e32 v22, v127
	v_mov_b32_e32 v21, v127
	v_mov_b32_e32 v20, v127
	v_mov_b32_e32 v19, v127
	v_mov_b32_e32 v18, v127
	v_mov_b32_e32 v17, v127
	v_mov_b32_e32 v16, v127
	v_mov_b32_e32 v7, v127
	v_mov_b32_e32 v6, v127
	v_mov_b32_e32 v5, v127
	v_mov_b32_e32 v4, v127
	v_mov_b32_e32 v3, v127
	v_mov_b32_e32 v2, v127
	s_waitcnt lgkmcnt(0)
	v_mov_b32_e32 v1, v127
	v_mov_b32_e32 v0, v127
	s_cbranch_vccnz .LBB0_270
	s_add_u32 s52, s52, 0x100
	s_addc_u32 s53, s53, 0
	s_add_u32 s56, s56, 0x100
	v_mov_b32_e32 v0, 0
	v_mov_b32_e32 v1, 0
	s_addc_u32 s57, s57, 0
	s_mov_b32 s12, 0
	v_pk_mov_b32 v[2:3], v[0:1], v[0:1]
	v_pk_mov_b32 v[4:5], v[0:1], v[0:1]
	v_pk_mov_b32 v[6:7], v[0:1], v[0:1]
	v_pk_mov_b32 v[16:17], v[0:1], v[0:1]
	v_pk_mov_b32 v[18:19], v[0:1], v[0:1]
	v_pk_mov_b32 v[20:21], v[0:1], v[0:1]
	v_pk_mov_b32 v[22:23], v[0:1], v[0:1]
	v_pk_mov_b32 v[32:33], v[0:1], v[0:1]
	v_pk_mov_b32 v[34:35], v[0:1], v[0:1]
	v_pk_mov_b32 v[36:37], v[0:1], v[0:1]
	v_pk_mov_b32 v[38:39], v[0:1], v[0:1]
	v_pk_mov_b32 v[48:49], v[0:1], v[0:1]
	v_pk_mov_b32 v[50:51], v[0:1], v[0:1]
	v_pk_mov_b32 v[52:53], v[0:1], v[0:1]
	v_pk_mov_b32 v[54:55], v[0:1], v[0:1]
	v_pk_mov_b32 v[8:9], v[0:1], v[0:1]
	v_pk_mov_b32 v[10:11], v[0:1], v[0:1]
	v_pk_mov_b32 v[12:13], v[0:1], v[0:1]
	v_pk_mov_b32 v[14:15], v[0:1], v[0:1]
	v_pk_mov_b32 v[24:25], v[0:1], v[0:1]
	v_pk_mov_b32 v[26:27], v[0:1], v[0:1]
	v_pk_mov_b32 v[28:29], v[0:1], v[0:1]
	v_pk_mov_b32 v[30:31], v[0:1], v[0:1]
	v_pk_mov_b32 v[40:41], v[0:1], v[0:1]
	v_pk_mov_b32 v[42:43], v[0:1], v[0:1]
	v_pk_mov_b32 v[44:45], v[0:1], v[0:1]
	v_pk_mov_b32 v[46:47], v[0:1], v[0:1]
	v_pk_mov_b32 v[56:57], v[0:1], v[0:1]
	v_pk_mov_b32 v[58:59], v[0:1], v[0:1]
	v_pk_mov_b32 v[60:61], v[0:1], v[0:1]
	v_pk_mov_b32 v[62:63], v[0:1], v[0:1]
	v_pk_mov_b32 v[64:65], v[0:1], v[0:1]
	v_pk_mov_b32 v[66:67], v[0:1], v[0:1]
	v_pk_mov_b32 v[68:69], v[0:1], v[0:1]
	v_pk_mov_b32 v[70:71], v[0:1], v[0:1]
	v_pk_mov_b32 v[80:81], v[0:1], v[0:1]
	v_pk_mov_b32 v[82:83], v[0:1], v[0:1]
	v_pk_mov_b32 v[84:85], v[0:1], v[0:1]
	v_pk_mov_b32 v[86:87], v[0:1], v[0:1]
	v_pk_mov_b32 v[96:97], v[0:1], v[0:1]
	v_pk_mov_b32 v[98:99], v[0:1], v[0:1]
	v_pk_mov_b32 v[100:101], v[0:1], v[0:1]
	v_pk_mov_b32 v[102:103], v[0:1], v[0:1]
	v_pk_mov_b32 v[112:113], v[0:1], v[0:1]
	v_pk_mov_b32 v[114:115], v[0:1], v[0:1]
	v_pk_mov_b32 v[116:117], v[0:1], v[0:1]
	v_pk_mov_b32 v[118:119], v[0:1], v[0:1]
	v_pk_mov_b32 v[72:73], v[0:1], v[0:1]
	v_pk_mov_b32 v[74:75], v[0:1], v[0:1]
	v_pk_mov_b32 v[76:77], v[0:1], v[0:1]
	v_pk_mov_b32 v[78:79], v[0:1], v[0:1]
	v_pk_mov_b32 v[88:89], v[0:1], v[0:1]
	v_pk_mov_b32 v[90:91], v[0:1], v[0:1]
	v_pk_mov_b32 v[92:93], v[0:1], v[0:1]
	v_pk_mov_b32 v[94:95], v[0:1], v[0:1]
	v_pk_mov_b32 v[104:105], v[0:1], v[0:1]
	v_pk_mov_b32 v[106:107], v[0:1], v[0:1]
	v_pk_mov_b32 v[108:109], v[0:1], v[0:1]
	v_pk_mov_b32 v[110:111], v[0:1], v[0:1]
	v_pk_mov_b32 v[120:121], v[0:1], v[0:1]
	v_pk_mov_b32 v[122:123], v[0:1], v[0:1]
	v_pk_mov_b32 v[124:125], v[0:1], v[0:1]
	v_pk_mov_b32 v[126:127], v[0:1], v[0:1]

; template <class Epi, class Ord>
; __device__ __forceinline__ void gemm_phase(LAS unsigned char* lds, const Gemm g, const Ord& S, const Epi& E) {
;     ...
; #pragma unroll
;         for (int a = 0; a < 2; ++a)
; #pragma unroll
;             for (int b = 0; b < 2; ++b)
; #pragma unroll
;                 for (int m = 0; m < 4; ++m)
; #pragma unroll
;                     for (int n = 0; n < 2; ++n) acc[a][b][m][n] = (f32x4){0.f, 0.f, 0.f, 0.f};
;         cur = nxt; cA = nA; cB = nB; ++ui;
.LBB0_496:
	v_mov_b32_e32 v127, 0
	v_mov_b32_e32 v126, 0
	s_andn2_b64 vcc, exec, s[16:17]
	v_pk_mov_b32 v[124:125], v[126:127], v[126:127]
	v_pk_mov_b32 v[122:123], v[126:127], v[126:127]
	v_pk_mov_b32 v[120:121], v[126:127], v[126:127]
	v_pk_mov_b32 v[110:111], v[126:127], v[126:127]
	v_pk_mov_b32 v[108:109], v[126:127], v[126:127]
	v_pk_mov_b32 v[106:107], v[126:127], v[126:127]
	v_pk_mov_b32 v[104:105], v[126:127], v[126:127]
	v_pk_mov_b32 v[94:95], v[126:127], v[126:127]
	v_pk_mov_b32 v[92:93], v[126:127], v[126:127]
	v_pk_mov_b32 v[90:91], v[126:127], v[126:127]
	v_pk_mov_b32 v[88:89], v[126:127], v[126:127]
	v_pk_mov_b32 v[78:79], v[126:127], v[126:127]
	v_pk_mov_b32 v[76:77], v[126:127], v[126:127]
	v_pk_mov_b32 v[74:75], v[126:127], v[126:127]
	v_pk_mov_b32 v[72:73], v[126:127], v[126:127]
	v_pk_mov_b32 v[118:119], v[126:127], v[126:127]
	v_pk_mov_b32 v[116:117], v[126:127], v[126:127]
	v_pk_mov_b32 v[114:115], v[126:127], v[126:127]
	v_pk_mov_b32 v[112:113], v[126:127], v[126:127]
	v_pk_mov_b32 v[102:103], v[126:127], v[126:127]
	v_pk_mov_b32 v[100:101], v[126:127], v[126:127]
	v_pk_mov_b32 v[98:99], v[126:127], v[126:127]
	v_pk_mov_b32 v[96:97], v[126:127], v[126:127]
	v_pk_mov_b32 v[86:87], v[126:127], v[126:127]
	v_pk_mov_b32 v[84:85], v[126:127], v[126:127]
	v_pk_mov_b32 v[82:83], v[126:127], v[126:127]
	v_pk_mov_b32 v[80:81], v[126:127], v[126:127]
	v_pk_mov_b32 v[70:71], v[126:127], v[126:127]
	v_pk_mov_b32 v[68:69], v[126:127], v[126:127]
	v_pk_mov_b32 v[66:67], v[126:127], v[126:127]
	v_pk_mov_b32 v[64:65], v[126:127], v[126:127]
	v_pk_mov_b32 v[62:63], v[126:127], v[126:127]
	v_pk_mov_b32 v[60:61], v[126:127], v[126:127]
	v_pk_mov_b32 v[58:59], v[126:127], v[126:127]
	v_pk_mov_b32 v[56:57], v[126:127], v[126:127]
	v_pk_mov_b32 v[46:47], v[126:127], v[126:127]
	v_pk_mov_b32 v[44:45], v[126:127], v[126:127]
	v_pk_mov_b32 v[42:43], v[126:127], v[126:127]
	v_pk_mov_b32 v[40:41], v[126:127], v[126:127]
	v_pk_mov_b32 v[30:31], v[126:127], v[126:127]
	v_pk_mov_b32 v[28:29], v[126:127], v[126:127]
	v_pk_mov_b32 v[26:27], v[126:127], v[126:127]
	v_pk_mov_b32 v[24:25], v[126:127], v[126:127]
	v_pk_mov_b32 v[14:15], v[126:127], v[126:127]
	v_pk_mov_b32 v[12:13], v[126:127], v[126:127]
	v_pk_mov_b32 v[10:11], v[126:127], v[126:127]
	v_pk_mov_b32 v[8:9], v[126:127], v[126:127]
	v_pk_mov_b32 v[54:55], v[126:127], v[126:127]
	v_pk_mov_b32 v[52:53], v[126:127], v[126:127]
	v_pk_mov_b32 v[50:51], v[126:127], v[126:127]
	v_pk_mov_b32 v[48:49], v[126:127], v[126:127]
	v_pk_mov_b32 v[38:39], v[126:127], v[126:127]
	v_pk_mov_b32 v[36:37], v[126:127], v[126:127]
	v_pk_mov_b32 v[34:35], v[126:127], v[126:127]
	v_pk_mov_b32 v[32:33], v[126:127], v[126:127]
	v_pk_mov_b32 v[22:23], v[126:127], v[126:127]
	v_pk_mov_b32 v[20:21], v[126:127], v[126:127]
	v_pk_mov_b32 v[18:19], v[126:127], v[126:127]
	v_pk_mov_b32 v[16:17], v[126:127], v[126:127]
	v_pk_mov_b32 v[6:7], v[126:127], v[126:127]
	v_pk_mov_b32 v[4:5], v[126:127], v[126:127]
	v_pk_mov_b32 v[2:3], v[126:127], v[126:127]
	v_pk_mov_b32 v[0:1], v[126:127], v[126:127]
	s_cbranch_vccnz .LBB0_484
	s_add_u32 s46, s46, 0x100
	s_addc_u32 s47, s47, 0
	s_add_u32 s48, s48, 0x100
	v_mov_b32_e32 v0, 0
	v_mov_b32_e32 v1, 0
	s_addc_u32 s49, s49, 0
	s_mov_b32 s12, 0
	v_pk_mov_b32 v[2:3], v[0:1], v[0:1]
	v_pk_mov_b32 v[4:5], v[0:1], v[0:1]
	v_pk_mov_b32 v[6:7], v[0:1], v[0:1]
	v_pk_mov_b32 v[16:17], v[0:1], v[0:1]
	v_pk_mov_b32 v[18:19], v[0:1], v[0:1]
	v_pk_mov_b32 v[20:21], v[0:1], v[0:1]
	v_pk_mov_b32 v[22:23], v[0:1], v[0:1]
	v_pk_mov_b32 v[32:33], v[0:1], v[0:1]
	v_pk_mov_b32 v[34:35], v[0:1], v[0:1]
	v_pk_mov_b32 v[36:37], v[0:1], v[0:1]
	v_pk_mov_b32 v[38:39], v[0:1], v[0:1]
	v_pk_mov_b32 v[48:49], v[0:1], v[0:1]
	v_pk_mov_b32 v[50:51], v[0:1], v[0:1]
	v_pk_mov_b32 v[52:53], v[0:1], v[0:1]
	v_pk_mov_b32 v[54:55], v[0:1], v[0:1]
	v_pk_mov_b32 v[8:9], v[0:1], v[0:1]
	v_pk_mov_b32 v[10:11], v[0:1], v[0:1]
	v_pk_mov_b32 v[12:13], v[0:1], v[0:1]
	v_pk_mov_b32 v[14:15], v[0:1], v[0:1]
	v_pk_mov_b32 v[24:25], v[0:1], v[0:1]
	v_pk_mov_b32 v[26:27], v[0:1], v[0:1]
	v_pk_mov_b32 v[28:29], v[0:1], v[0:1]
	v_pk_mov_b32 v[30:31], v[0:1], v[0:1]
	v_pk_mov_b32 v[40:41], v[0:1], v[0:1]
	v_pk_mov_b32 v[42:43], v[0:1], v[0:1]
	v_pk_mov_b32 v[44:45], v[0:1], v[0:1]
	v_pk_mov_b32 v[46:47], v[0:1], v[0:1]
	v_pk_mov_b32 v[56:57], v[0:1], v[0:1]
	v_pk_mov_b32 v[58:59], v[0:1], v[0:1]
	v_pk_mov_b32 v[60:61], v[0:1], v[0:1]
	v_pk_mov_b32 v[62:63], v[0:1], v[0:1]
	v_pk_mov_b32 v[64:65], v[0:1], v[0:1]
	v_pk_mov_b32 v[66:67], v[0:1], v[0:1]
	v_pk_mov_b32 v[68:69], v[0:1], v[0:1]
	v_pk_mov_b32 v[70:71], v[0:1], v[0:1]
	v_pk_mov_b32 v[80:81], v[0:1], v[0:1]
	v_pk_mov_b32 v[82:83], v[0:1], v[0:1]
	v_pk_mov_b32 v[84:85], v[0:1], v[0:1]
	v_pk_mov_b32 v[86:87], v[0:1], v[0:1]
	v_pk_mov_b32 v[96:97], v[0:1], v[0:1]
	v_pk_mov_b32 v[98:99], v[0:1], v[0:1]
	v_pk_mov_b32 v[100:101], v[0:1], v[0:1]
	v_pk_mov_b32 v[102:103], v[0:1], v[0:1]
	v_pk_mov_b32 v[112:113], v[0:1], v[0:1]
	v_pk_mov_b32 v[114:115], v[0:1], v[0:1]
	v_pk_mov_b32 v[116:117], v[0:1], v[0:1]
	v_pk_mov_b32 v[118:119], v[0:1], v[0:1]
	v_pk_mov_b32 v[72:73], v[0:1], v[0:1]
	v_pk_mov_b32 v[74:75], v[0:1], v[0:1]
	v_pk_mov_b32 v[76:77], v[0:1], v[0:1]
	v_pk_mov_b32 v[78:79], v[0:1], v[0:1]
	v_pk_mov_b32 v[88:89], v[0:1], v[0:1]
	v_pk_mov_b32 v[90:91], v[0:1], v[0:1]
	v_pk_mov_b32 v[92:93], v[0:1], v[0:1]
	v_pk_mov_b32 v[94:95], v[0:1], v[0:1]
	v_pk_mov_b32 v[104:105], v[0:1], v[0:1]
	v_pk_mov_b32 v[106:107], v[0:1], v[0:1]
	v_pk_mov_b32 v[108:109], v[0:1], v[0:1]
	v_pk_mov_b32 v[110:111], v[0:1], v[0:1]
	v_pk_mov_b32 v[120:121], v[0:1], v[0:1]
	v_pk_mov_b32 v[122:123], v[0:1], v[0:1]
	v_pk_mov_b32 v[124:125], v[0:1], v[0:1]
	v_pk_mov_b32 v[126:127], v[0:1], v[0:1]

; template <class Epi, class Ord>
; __device__ __forceinline__ void gemm_phase(LAS unsigned char* lds, const Gemm g, const Ord& S, const Epi& E) {
;     ...
; #pragma unroll
;         for (int a = 0; a < 2; ++a)
; #pragma unroll
;             for (int b = 0; b < 2; ++b)
; #pragma unroll
;                 for (int m = 0; m < 4; ++m)
; #pragma unroll
;                     for (int n = 0; n < 2; ++n) acc[a][b][m][n] = (f32x4){0.f, 0.f, 0.f, 0.f};
;         cur = nxt; cA = nA; cB = nB; ++ui;
.LBB0_574:
	v_mov_b32_e32 v127, 0
	s_andn2_b64 vcc, exec, s[10:11]
	v_mov_b32_e32 v126, v127
	v_mov_b32_e32 v125, v127
	v_mov_b32_e32 v124, v127
	v_mov_b32_e32 v123, v127
	v_mov_b32_e32 v122, v127
	v_mov_b32_e32 v121, v127
	v_mov_b32_e32 v120, v127
	v_mov_b32_e32 v111, v127
	v_mov_b32_e32 v110, v127
	v_mov_b32_e32 v109, v127
	v_mov_b32_e32 v108, v127
	v_mov_b32_e32 v107, v127
	v_mov_b32_e32 v106, v127
	v_mov_b32_e32 v105, v127
	v_mov_b32_e32 v104, v127
	v_mov_b32_e32 v95, v127
	v_mov_b32_e32 v94, v127
	v_mov_b32_e32 v93, v127
	v_mov_b32_e32 v92, v127
	v_mov_b32_e32 v91, v127
	v_mov_b32_e32 v90, v127
	v_mov_b32_e32 v89, v127
	v_mov_b32_e32 v88, v127
	v_mov_b32_e32 v79, v127
	v_mov_b32_e32 v78, v127
	v_mov_b32_e32 v77, v127
	v_mov_b32_e32 v76, v127
	v_mov_b32_e32 v75, v127
	v_mov_b32_e32 v74, v127
	v_mov_b32_e32 v73, v127
	v_mov_b32_e32 v72, v127
	v_mov_b32_e32 v119, v127
	v_mov_b32_e32 v118, v127
	v_mov_b32_e32 v117, v127
	v_mov_b32_e32 v116, v127
	v_mov_b32_e32 v115, v127
	v_mov_b32_e32 v114, v127
	v_mov_b32_e32 v113, v127
	v_mov_b32_e32 v112, v127
	v_mov_b32_e32 v103, v127
	v_mov_b32_e32 v102, v127
	v_mov_b32_e32 v101, v127
	v_mov_b32_e32 v100, v127
	v_mov_b32_e32 v99, v127
	v_mov_b32_e32 v98, v127
	v_mov_b32_e32 v97, v127
	v_mov_b32_e32 v96, v127
	v_mov_b32_e32 v87, v127
	v_mov_b32_e32 v86, v127
	v_mov_b32_e32 v85, v127
	v_mov_b32_e32 v84, v127
	v_mov_b32_e32 v83, v127
	v_mov_b32_e32 v82, v127
	v_mov_b32_e32 v81, v127
	v_mov_b32_e32 v80, v127
	v_mov_b32_e32 v71, v127
	v_mov_b32_e32 v70, v127
	v_mov_b32_e32 v69, v127
	v_mov_b32_e32 v68, v127
	v_mov_b32_e32 v67, v127
	v_mov_b32_e32 v66, v127
	v_mov_b32_e32 v65, v127
	v_mov_b32_e32 v64, v127
	v_mov_b32_e32 v63, v127
	v_mov_b32_e32 v62, v127
	v_mov_b32_e32 v61, v127
	v_mov_b32_e32 v60, v127
	v_mov_b32_e32 v59, v127
	v_mov_b32_e32 v58, v127
	v_mov_b32_e32 v57, v127
	v_mov_b32_e32 v56, v127
	v_mov_b32_e32 v47, v127
	v_mov_b32_e32 v46, v127
	v_mov_b32_e32 v45, v127
	v_mov_b32_e32 v44, v127
	v_mov_b32_e32 v43, v127
	v_mov_b32_e32 v42, v127
	v_mov_b32_e32 v41, v127
	v_mov_b32_e32 v40, v127
	v_mov_b32_e32 v31, v127
	v_mov_b32_e32 v30, v127
	v_mov_b32_e32 v29, v127
	v_mov_b32_e32 v28, v127
	v_mov_b32_e32 v27, v127
	v_mov_b32_e32 v26, v127
	v_mov_b32_e32 v25, v127
	v_mov_b32_e32 v24, v127
	v_mov_b32_e32 v15, v127
	v_mov_b32_e32 v14, v127
	v_mov_b32_e32 v13, v127
	v_mov_b32_e32 v12, v127
	v_mov_b32_e32 v11, v127
	v_mov_b32_e32 v10, v127
	v_mov_b32_e32 v9, v127
	v_mov_b32_e32 v8, v127
	v_mov_b32_e32 v55, v127
	v_mov_b32_e32 v54, v127
	v_mov_b32_e32 v53, v127
	v_mov_b32_e32 v52, v127
	v_mov_b32_e32 v51, v127
	v_mov_b32_e32 v50, v127
	v_mov_b32_e32 v49, v127
	v_mov_b32_e32 v48, v127
	v_mov_b32_e32 v39, v127
	v_mov_b32_e32 v38, v127
	v_mov_b32_e32 v37, v127
	v_mov_b32_e32 v36, v127
	v_mov_b32_e32 v35, v127
	v_mov_b32_e32 v34, v127
	v_mov_b32_e32 v33, v127
	v_mov_b32_e32 v32, v127
	v_mov_b32_e32 v23, v127
	v_mov_b32_e32 v22, v127
	v_mov_b32_e32 v21, v127
	v_mov_b32_e32 v20, v127
	v_mov_b32_e32 v19, v127
	v_mov_b32_e32 v18, v127
	v_mov_b32_e32 v17, v127
	v_mov_b32_e32 v16, v127
	v_mov_b32_e32 v7, v127
	v_mov_b32_e32 v6, v127
	v_mov_b32_e32 v5, v127
	v_mov_b32_e32 v4, v127
	v_mov_b32_e32 v3, v127
	v_mov_b32_e32 v2, v127
	s_waitcnt lgkmcnt(0)
	v_mov_b32_e32 v1, v127
	v_mov_b32_e32 v0, v127
	s_cbranch_vccnz .LBB0_577
	s_add_u32 s90, s16, 0x100
	s_addc_u32 s91, s17, 0
	s_add_u32 s46, s46, 0x100
	v_mov_b32_e32 v0, 0
	v_mov_b32_e32 v1, 0
	s_addc_u32 s47, s47, 0
	s_mov_b32 s12, 0
	v_pk_mov_b32 v[2:3], v[0:1], v[0:1]
	v_pk_mov_b32 v[4:5], v[0:1], v[0:1]
	v_pk_mov_b32 v[6:7], v[0:1], v[0:1]
	v_pk_mov_b32 v[16:17], v[0:1], v[0:1]
	v_pk_mov_b32 v[18:19], v[0:1], v[0:1]
	v_pk_mov_b32 v[20:21], v[0:1], v[0:1]
	v_pk_mov_b32 v[22:23], v[0:1], v[0:1]
	v_pk_mov_b32 v[32:33], v[0:1], v[0:1]
	v_pk_mov_b32 v[34:35], v[0:1], v[0:1]
	v_pk_mov_b32 v[36:37], v[0:1], v[0:1]
	v_pk_mov_b32 v[38:39], v[0:1], v[0:1]
	v_pk_mov_b32 v[48:49], v[0:1], v[0:1]
	v_pk_mov_b32 v[50:51], v[0:1], v[0:1]
	v_pk_mov_b32 v[52:53], v[0:1], v[0:1]
	v_pk_mov_b32 v[54:55], v[0:1], v[0:1]
	v_pk_mov_b32 v[8:9], v[0:1], v[0:1]
	v_pk_mov_b32 v[10:11], v[0:1], v[0:1]
	v_pk_mov_b32 v[12:13], v[0:1], v[0:1]
	v_pk_mov_b32 v[14:15], v[0:1], v[0:1]
	v_pk_mov_b32 v[24:25], v[0:1], v[0:1]
	v_pk_mov_b32 v[26:27], v[0:1], v[0:1]
	v_pk_mov_b32 v[28:29], v[0:1], v[0:1]
	v_pk_mov_b32 v[30:31], v[0:1], v[0:1]
	v_pk_mov_b32 v[40:41], v[0:1], v[0:1]
	v_pk_mov_b32 v[42:43], v[0:1], v[0:1]
	v_pk_mov_b32 v[44:45], v[0:1], v[0:1]
	v_pk_mov_b32 v[46:47], v[0:1], v[0:1]
	v_pk_mov_b32 v[56:57], v[0:1], v[0:1]
	v_pk_mov_b32 v[58:59], v[0:1], v[0:1]
	v_pk_mov_b32 v[60:61], v[0:1], v[0:1]
	v_pk_mov_b32 v[62:63], v[0:1], v[0:1]
	v_pk_mov_b32 v[64:65], v[0:1], v[0:1]
	v_pk_mov_b32 v[66:67], v[0:1], v[0:1]
	v_pk_mov_b32 v[68:69], v[0:1], v[0:1]
	v_pk_mov_b32 v[70:71], v[0:1], v[0:1]
	v_pk_mov_b32 v[80:81], v[0:1], v[0:1]
	v_pk_mov_b32 v[82:83], v[0:1], v[0:1]
	v_pk_mov_b32 v[84:85], v[0:1], v[0:1]
	v_pk_mov_b32 v[86:87], v[0:1], v[0:1]
	v_pk_mov_b32 v[96:97], v[0:1], v[0:1]
	v_pk_mov_b32 v[98:99], v[0:1], v[0:1]
	v_pk_mov_b32 v[100:101], v[0:1], v[0:1]
	v_pk_mov_b32 v[102:103], v[0:1], v[0:1]
	v_pk_mov_b32 v[112:113], v[0:1], v[0:1]
	v_pk_mov_b32 v[114:115], v[0:1], v[0:1]
	v_pk_mov_b32 v[116:117], v[0:1], v[0:1]
	v_pk_mov_b32 v[118:119], v[0:1], v[0:1]
	v_pk_mov_b32 v[72:73], v[0:1], v[0:1]
	v_pk_mov_b32 v[74:75], v[0:1], v[0:1]
	v_pk_mov_b32 v[76:77], v[0:1], v[0:1]
	v_pk_mov_b32 v[78:79], v[0:1], v[0:1]
	v_pk_mov_b32 v[88:89], v[0:1], v[0:1]
	v_pk_mov_b32 v[90:91], v[0:1], v[0:1]
	v_pk_mov_b32 v[92:93], v[0:1], v[0:1]
	v_pk_mov_b32 v[94:95], v[0:1], v[0:1]
	v_pk_mov_b32 v[104:105], v[0:1], v[0:1]
	v_pk_mov_b32 v[106:107], v[0:1], v[0:1]
	v_pk_mov_b32 v[108:109], v[0:1], v[0:1]
	v_pk_mov_b32 v[110:111], v[0:1], v[0:1]
	v_pk_mov_b32 v[120:121], v[0:1], v[0:1]
	v_pk_mov_b32 v[122:123], v[0:1], v[0:1]
	v_pk_mov_b32 v[124:125], v[0:1], v[0:1]
	v_pk_mov_b32 v[126:127], v[0:1], v[0:1]

; __device__ __forceinline__ unsigned cvt_pk_bf16(float lo, float hi) { const f32x2 v = {lo, hi}; return __builtin_bit_cast(unsigned, __builtin_convertvector(v, bfx2_t)); }
;     __device__ __forceinline__ void operator()(const AccT& acc, const Unit& u, int ui, int wr, int wc, int fr, int fq) const {
;         const int col = u.pn * 128 + wc * 32 + 8 * fq;
; #pragma unroll
;         for (int ai = 0; ai < 2; ++ai)
; #pragma unroll
;             for (int m = 0; m < 4; ++m) {
;                 const int rl = ai * 128 + wr * 64 + m * 16 + fr; const float r = rs[((u.pm >> 3) & 3) * 256 + rl];
;                 const float nr = -1.4426950408889634f * r, r2 = r * r;
;                 unsigned w[4];
; #pragma unroll
;                 for (int n = 0; n < 2; ++n)
; #pragma unroll
;                     for (int hlf = 0; hlf < 2; ++hlf) {
;                         const f32x2 a = {acc[ai][0][m][n][2 * hlf], acc[ai][0][m][n][2 * hlf + 1]}, b = {acc[ai][1][m][n][2 * hlf], acc[ai][1][m][n][2 * hlf + 1]};
;                         const f32x2 t = a * nr;
;                         f32x2 d; d.x = __builtin_amdgcn_exp2f(t.x); d.y = __builtin_amdgcn_exp2f(t.y); d = d + 1.0f;
;                         f32x2 q; q.x = __builtin_amdgcn_rcpf(d.x); q.y = __builtin_amdgcn_rcpf(d.y);
;                         const f32x2 o = ((a * b) * r2) * q;
;                         w[n * 2 + hlf] = cvt_pk_bf16(o.x, o.y);
;                     }
;                 u32x4 wv; wv.x = w[0]; wv.y = w[1]; wv.z = w[2]; wv.w = w[3];
;                 *GP(u32x4, O + (size_t)(u.pm * 256 + rl) * FF + col) = wv;
.LBB0_603:
	s_lshl_b32 s13, s72, 7
	s_and_b32 s13, s13, 0xc00
	v_add_u32_e32 v140, s13, v138
	ds_read2_b32 v[144:145], v140 offset1:16
	ds_read2_b32 v[174:175], v140 offset0:32 offset1:48
	ds_read2_b32 v[176:177], v140 offset0:128 offset1:144
	ds_read2_b32 v[178:179], v140 offset0:160 offset1:176
	v_pk_mul_f32 v[126:127], v[126:127], v[122:123]
	v_pk_mul_f32 v[118:119], v[118:119], v[114:115]
	v_lshl_or_b32 v142, s73, 7, v137
	s_lshl_b32 s12, s72, 8
	s_waitcnt lgkmcnt(0)
	v_mul_f32_e32 v146, 0xbfb8aa3b, v144
	v_pk_mul_f32 v[148:149], v[120:121], v[146:147] op_sel_hi:[1,0]
	v_pk_mul_f32 v[122:123], v[122:123], v[146:147] op_sel_hi:[1,0]
	v_exp_f32_e32 v148, v148
	v_exp_f32_e32 v149, v149
	v_exp_f32_e32 v122, v122
	v_exp_f32_e32 v123, v123
	v_mul_f32_e32 v144, v144, v144
	v_pk_add_f32 v[148:149], v[148:149], 1.0 op_sel_hi:[1,0]
	v_pk_mul_f32 v[120:121], v[124:125], v[120:121]
	v_pk_add_f32 v[122:123], v[122:123], 1.0 op_sel_hi:[1,0]
	v_rcp_f32_e32 v148, v148
	v_rcp_f32_e32 v149, v149
	v_rcp_f32_e32 v122, v122
	v_rcp_f32_e32 v123, v123
	v_pk_mul_f32 v[120:121], v[120:121], v[144:145] op_sel_hi:[1,0]
	v_pk_mul_f32 v[124:125], v[126:127], v[144:145] op_sel_hi:[1,0]
	v_pk_mul_f32 v[120:121], v[120:121], v[148:149]
	v_pk_mul_f32 v[122:123], v[124:125], v[122:123]
	v_cvt_pk_bf16_f32 v120, v120, v121
	v_cvt_pk_bf16_f32 v121, v122, v123
	v_pk_mul_f32 v[122:123], v[112:113], v[146:147] op_sel_hi:[1,0]
	v_pk_mul_f32 v[112:113], v[116:117], v[112:113]
	v_exp_f32_e32 v122, v122
	v_exp_f32_e32 v123, v123
	v_pk_mul_f32 v[112:113], v[112:113], v[144:145] op_sel_hi:[1,0]
	v_ashrrev_i32_e32 v143, 31, v142
	v_add_u32_e32 v116, s12, v132
	v_pk_add_f32 v[122:123], v[122:123], 1.0 op_sel_hi:[1,0]
	v_pk_mul_f32 v[110:111], v[110:111], v[106:107]
	v_rcp_f32_e32 v122, v122
	v_rcp_f32_e32 v123, v123
	v_pk_mul_f32 v[102:103], v[102:103], v[98:99]
	v_pk_mul_f32 v[94:95], v[94:95], v[90:91]
	v_pk_mul_f32 v[86:87], v[86:87], v[82:83]
	v_pk_mul_f32 v[112:113], v[112:113], v[122:123]
	v_pk_mul_f32 v[78:79], v[78:79], v[74:75]
	v_cvt_pk_bf16_f32 v122, v112, v113
	v_pk_mul_f32 v[112:113], v[114:115], v[146:147] op_sel_hi:[1,0]
	v_pk_mul_f32 v[114:115], v[118:119], v[144:145] op_sel_hi:[1,0]
	v_exp_f32_e32 v112, v112
	v_exp_f32_e32 v113, v113
	v_pk_mul_f32 v[70:71], v[70:71], v[66:67]
	v_pk_mul_f32 v[62:63], v[62:63], v[58:59]
	v_pk_mul_f32 v[54:55], v[54:55], v[50:51]
	v_pk_add_f32 v[112:113], v[112:113], 1.0 op_sel_hi:[1,0]
	v_pk_mul_f32 v[46:47], v[46:47], v[42:43]
	v_rcp_f32_e32 v112, v112
	v_rcp_f32_e32 v113, v113
	v_pk_mul_f32 v[38:39], v[38:39], v[34:35]
	v_pk_mul_f32 v[30:31], v[30:31], v[26:27]
	v_pk_mul_f32 v[22:23], v[22:23], v[18:19]
	v_pk_mul_f32 v[112:113], v[114:115], v[112:113]
	v_lshlrev_b64 v[114:115], 1, v[142:143]
	v_cvt_pk_bf16_f32 v123, v112, v113
	v_mov_b64_e32 v[112:113], s[14:15]
	v_mad_i64_i32 v[118:119], s[20:21], v116, s35, v[112:113]
	v_lshl_add_u64 v[118:119], v[118:119], 0, v[114:115]
	global_store_dwordx4 v[118:119], v[120:123], off
	v_mul_f32_e32 v118, 0xbfb8aa3b, v145
	v_pk_mul_f32 v[106:107], v[106:107], v[118:119] op_sel_hi:[1,0]
	v_pk_mul_f32 v[122:123], v[104:105], v[118:119] op_sel_hi:[1,0]
	v_exp_f32_e32 v106, v106
	v_exp_f32_e32 v122, v122
	v_exp_f32_e32 v123, v123
	v_exp_f32_e32 v107, v107
	v_mul_f32_e32 v120, v145, v145
	v_pk_mul_f32 v[104:105], v[108:109], v[104:105]
	v_pk_add_f32 v[122:123], v[122:123], 1.0 op_sel_hi:[1,0]
	v_pk_add_f32 v[106:107], v[106:107], 1.0 op_sel_hi:[1,0]
	v_rcp_f32_e32 v122, v122
	v_rcp_f32_e32 v123, v123
	v_rcp_f32_e32 v106, v106
	v_rcp_f32_e32 v107, v107
	v_pk_mul_f32 v[104:105], v[104:105], v[120:121] op_sel_hi:[1,0]
	v_pk_mul_f32 v[108:109], v[110:111], v[120:121] op_sel_hi:[1,0]
	v_pk_mul_f32 v[104:105], v[104:105], v[122:123]
	v_pk_mul_f32 v[106:107], v[108:109], v[106:107]
	v_cvt_pk_bf16_f32 v104, v104, v105
	v_cvt_pk_bf16_f32 v105, v106, v107
	v_pk_mul_f32 v[106:107], v[96:97], v[118:119] op_sel_hi:[1,0]
	v_pk_mul_f32 v[96:97], v[100:101], v[96:97]
	v_exp_f32_e32 v106, v106
	v_exp_f32_e32 v107, v107
	v_pk_mul_f32 v[96:97], v[96:97], v[120:121] op_sel_hi:[1,0]
	v_pk_mul_f32 v[14:15], v[14:15], v[10:11]
	v_pk_mul_f32 v[6:7], v[6:7], v[2:3]
	v_pk_add_f32 v[106:107], v[106:107], 1.0 op_sel_hi:[1,0]
	s_and_b64 vcc, exec, s[18:19]
	v_rcp_f32_e32 v106, v106
	v_rcp_f32_e32 v107, v107
	s_mov_b32 s73, s70
	s_mov_b32 s72, s71
	s_mov_b64 s[44:45], s[42:43]
	v_pk_mul_f32 v[96:97], v[96:97], v[106:107]
	s_mov_b64 s[46:47], s[38:39]
	v_cvt_pk_bf16_f32 v106, v96, v97
	v_pk_mul_f32 v[96:97], v[98:99], v[118:119] op_sel_hi:[1,0]
	v_pk_mul_f32 v[98:99], v[102:103], v[120:121] op_sel_hi:[1,0]
	v_exp_f32_e32 v96, v96
	v_exp_f32_e32 v97, v97
	s_mov_b32 s18, s69
	v_pk_add_f32 v[96:97], v[96:97], 1.0 op_sel_hi:[1,0]
	s_nop 0
	v_rcp_f32_e32 v96, v96
	v_rcp_f32_e32 v97, v97
	s_nop 0
	v_pk_mul_f32 v[96:97], v[98:99], v[96:97]
	s_nop 0
	v_cvt_pk_bf16_f32 v107, v96, v97
	v_add_u32_e32 v96, s12, v134
	v_mad_i64_i32 v[96:97], s[20:21], v96, s35, v[112:113]
	v_lshl_add_u64 v[96:97], v[96:97], 0, v[114:115]
	global_store_dwordx4 v[96:97], v[104:107], off
	v_mov_b32_e32 v96, v174
	v_mov_b32_e32 v97, v175
	s_waitcnt lgkmcnt(0)
; __device__ __forceinline__ unsigned cvt_pk_bf16(float lo, float hi) { const f32x2 v = {lo, hi}; return __builtin_bit_cast(unsigned, __builtin_convertvector(v, bfx2_t)); }
;     __device__ __forceinline__ void operator()(const AccT& acc, const Unit& u, int ui, int wr, int wc, int fr, int fq) const {
;     ...
;                 const int rl = ai * 128 + wr * 64 + m * 16 + fr; const float r = rs[((u.pm >> 3) & 3) * 256 + rl];
;                 const float nr = -1.4426950408889634f * r, r2 = r * r;
;                 unsigned w[4];
; #pragma unroll
;                 for (int n = 0; n < 2; ++n)
; #pragma unroll
;                     for (int hlf = 0; hlf < 2; ++hlf) {
;                         const f32x2 a = {acc[ai][0][m][n][2 * hlf], acc[ai][0][m][n][2 * hlf + 1]}, b = {acc[ai][1][m][n][2 * hlf], acc[ai][1][m][n][2 * hlf + 1]};
;                         const f32x2 t = a * nr;
;                         f32x2 d; d.x = __builtin_amdgcn_exp2f(t.x); d.y = __builtin_amdgcn_exp2f(t.y); d = d + 1.0f;
;                         f32x2 q; q.x = __builtin_amdgcn_rcpf(d.x); q.y = __builtin_amdgcn_rcpf(d.y);
;                         const f32x2 o = ((a * b) * r2) * q;
;                         w[n * 2 + hlf] = cvt_pk_bf16(o.x, o.y);
;                     }
;                 u32x4 wv; wv.x = w[0]; wv.y = w[1]; wv.z = w[2]; wv.w = w[3];
;                 *GP(u32x4, O + (size_t)(u.pm * 256 + rl) * FF + col) = wv;
	v_mul_f32_e32 v98, 0xbfb8aa3b, v96
	v_pk_mul_f32 v[100:101], v[88:89], v[98:99] op_sel_hi:[1,0]
	v_pk_mul_f32 v[90:91], v[90:91], v[98:99] op_sel_hi:[1,0]
	v_exp_f32_e32 v100, v100
	v_exp_f32_e32 v101, v101
	v_exp_f32_e32 v90, v90
	v_exp_f32_e32 v91, v91
	v_mul_f32_e32 v96, v96, v96
	v_pk_add_f32 v[100:101], v[100:101], 1.0 op_sel_hi:[1,0]
	v_pk_mul_f32 v[88:89], v[92:93], v[88:89]
	v_pk_add_f32 v[90:91], v[90:91], 1.0 op_sel_hi:[1,0]
	v_rcp_f32_e32 v100, v100
	v_rcp_f32_e32 v101, v101
	v_rcp_f32_e32 v90, v90
	v_rcp_f32_e32 v91, v91
	v_pk_mul_f32 v[88:89], v[88:89], v[96:97] op_sel_hi:[1,0]
	v_pk_mul_f32 v[92:93], v[94:95], v[96:97] op_sel_hi:[1,0]
	v_pk_mul_f32 v[88:89], v[88:89], v[100:101]
	v_pk_mul_f32 v[90:91], v[92:93], v[90:91]
	v_cvt_pk_bf16_f32 v88, v88, v89
	v_cvt_pk_bf16_f32 v89, v90, v91
	v_pk_mul_f32 v[90:91], v[80:81], v[98:99] op_sel_hi:[1,0]
	v_pk_mul_f32 v[80:81], v[84:85], v[80:81]
	v_exp_f32_e32 v90, v90
	v_exp_f32_e32 v91, v91
	v_pk_mul_f32 v[80:81], v[80:81], v[96:97] op_sel_hi:[1,0]
	v_pk_add_f32 v[90:91], v[90:91], 1.0 op_sel_hi:[1,0]
	s_nop 0
	v_rcp_f32_e32 v90, v90
	v_rcp_f32_e32 v91, v91
	s_nop 0
	v_pk_mul_f32 v[80:81], v[80:81], v[90:91]
	s_nop 0
	v_cvt_pk_bf16_f32 v90, v80, v81
	v_pk_mul_f32 v[80:81], v[82:83], v[98:99] op_sel_hi:[1,0]
	v_pk_mul_f32 v[82:83], v[86:87], v[96:97] op_sel_hi:[1,0]
	v_exp_f32_e32 v80, v80
	v_exp_f32_e32 v81, v81
	s_nop 0
	v_pk_add_f32 v[80:81], v[80:81], 1.0 op_sel_hi:[1,0]
	s_nop 0
	v_rcp_f32_e32 v80, v80
	v_rcp_f32_e32 v81, v81
	s_nop 0
	v_pk_mul_f32 v[80:81], v[82:83], v[80:81]
	s_nop 0
	v_cvt_pk_bf16_f32 v91, v80, v81
	v_add_u32_e32 v80, s12, v135
	v_mad_i64_i32 v[80:81], s[20:21], v80, s35, v[112:113]
	v_lshl_add_u64 v[80:81], v[80:81], 0, v[114:115]
	global_store_dwordx4 v[80:81], v[88:91], off
	v_mul_f32_e32 v80, 0xbfb8aa3b, v97
	v_pk_mul_f32 v[84:85], v[72:73], v[80:81] op_sel_hi:[1,0]
	v_pk_mul_f32 v[74:75], v[74:75], v[80:81] op_sel_hi:[1,0]
	v_exp_f32_e32 v84, v84
	v_exp_f32_e32 v85, v85
	v_exp_f32_e32 v74, v74
	v_exp_f32_e32 v75, v75
	v_mul_f32_e32 v82, v97, v97
	v_pk_add_f32 v[84:85], v[84:85], 1.0 op_sel_hi:[1,0]
	v_pk_mul_f32 v[72:73], v[76:77], v[72:73]
	v_pk_add_f32 v[74:75], v[74:75], 1.0 op_sel_hi:[1,0]
	v_rcp_f32_e32 v84, v84
	v_rcp_f32_e32 v85, v85
	v_rcp_f32_e32 v74, v74
	v_rcp_f32_e32 v75, v75
	v_pk_mul_f32 v[72:73], v[72:73], v[82:83] op_sel_hi:[1,0]
	v_pk_mul_f32 v[76:77], v[78:79], v[82:83] op_sel_hi:[1,0]
	v_pk_mul_f32 v[72:73], v[72:73], v[84:85]
	v_pk_mul_f32 v[74:75], v[76:77], v[74:75]
	v_cvt_pk_bf16_f32 v72, v72, v73
	v_cvt_pk_bf16_f32 v73, v74, v75
	v_pk_mul_f32 v[74:75], v[64:65], v[80:81] op_sel_hi:[1,0]
	v_pk_mul_f32 v[64:65], v[68:69], v[64:65]
	v_exp_f32_e32 v74, v74
	v_exp_f32_e32 v75, v75
	v_pk_mul_f32 v[64:65], v[64:65], v[82:83] op_sel_hi:[1,0]
	v_pk_add_f32 v[74:75], v[74:75], 1.0 op_sel_hi:[1,0]
	s_nop 0
	v_rcp_f32_e32 v74, v74
	v_rcp_f32_e32 v75, v75
	s_nop 0
	v_pk_mul_f32 v[64:65], v[64:65], v[74:75]
	s_nop 0
	v_cvt_pk_bf16_f32 v74, v64, v65
	v_pk_mul_f32 v[64:65], v[66:67], v[80:81] op_sel_hi:[1,0]
	v_pk_mul_f32 v[66:67], v[70:71], v[82:83] op_sel_hi:[1,0]
	v_exp_f32_e32 v64, v64
	v_exp_f32_e32 v65, v65
	s_nop 0
	v_pk_add_f32 v[64:65], v[64:65], 1.0 op_sel_hi:[1,0]
	s_nop 0
	v_rcp_f32_e32 v64, v64
	v_rcp_f32_e32 v65, v65
	s_nop 0
	v_pk_mul_f32 v[64:65], v[66:67], v[64:65]
	s_nop 0
	v_cvt_pk_bf16_f32 v75, v64, v65
	v_add_u32_e32 v64, s12, v136
	v_mad_i64_i32 v[64:65], s[12:13], v64, s35, v[112:113]
	v_lshl_add_u64 v[64:65], v[64:65], 0, v[114:115]
	global_store_dwordx4 v[64:65], v[72:75], off
	v_mov_b32_e32 v64, v176
	v_mov_b32_e32 v65, v177
	s_waitcnt lgkmcnt(0)
	v_mul_f32_e32 v66, 0xbfb8aa3b, v64
	v_pk_mul_f32 v[68:69], v[56:57], v[66:67] op_sel_hi:[1,0]
	v_pk_mul_f32 v[58:59], v[58:59], v[66:67] op_sel_hi:[1,0]
	v_exp_f32_e32 v68, v68
	v_exp_f32_e32 v69, v69
	v_exp_f32_e32 v58, v58
	v_exp_f32_e32 v59, v59
	v_mul_f32_e32 v64, v64, v64
	v_pk_add_f32 v[68:69], v[68:69], 1.0 op_sel_hi:[1,0]
	v_pk_mul_f32 v[56:57], v[60:61], v[56:57]
	v_pk_add_f32 v[58:59], v[58:59], 1.0 op_sel_hi:[1,0]
	v_rcp_f32_e32 v68, v68
	v_rcp_f32_e32 v69, v69
	v_rcp_f32_e32 v58, v58
	v_rcp_f32_e32 v59, v59
	v_pk_mul_f32 v[56:57], v[56:57], v[64:65] op_sel_hi:[1,0]
	v_pk_mul_f32 v[60:61], v[62:63], v[64:65] op_sel_hi:[1,0]
	v_pk_mul_f32 v[56:57], v[56:57], v[68:69]
	v_pk_mul_f32 v[58:59], v[60:61], v[58:59]
	v_cvt_pk_bf16_f32 v56, v56, v57
	v_cvt_pk_bf16_f32 v57, v58, v59
	v_pk_mul_f32 v[58:59], v[48:49], v[66:67] op_sel_hi:[1,0]
	v_pk_mul_f32 v[48:49], v[52:53], v[48:49]
	v_exp_f32_e32 v58, v58
	v_exp_f32_e32 v59, v59
	v_pk_mul_f32 v[48:49], v[48:49], v[64:65] op_sel_hi:[1,0]
	v_pk_add_f32 v[58:59], v[58:59], 1.0 op_sel_hi:[1,0]
	s_nop 0
	v_rcp_f32_e32 v58, v58
	v_rcp_f32_e32 v59, v59
	s_nop 0
	v_pk_mul_f32 v[48:49], v[48:49], v[58:59]
	s_nop 0
	v_cvt_pk_bf16_f32 v58, v48, v49
	v_pk_mul_f32 v[48:49], v[50:51], v[66:67] op_sel_hi:[1,0]
	v_pk_mul_f32 v[50:51], v[54:55], v[64:65] op_sel_hi:[1,0]
	v_exp_f32_e32 v48, v48
	v_exp_f32_e32 v49, v49
	s_nop 0
	v_pk_add_f32 v[48:49], v[48:49], 1.0 op_sel_hi:[1,0]
	s_nop 0
	v_rcp_f32_e32 v48, v48
	v_rcp_f32_e32 v49, v49
	s_nop 0
	v_pk_mul_f32 v[48:49], v[50:51], v[48:49]
	s_nop 0
	v_cvt_pk_bf16_f32 v59, v48, v49
	v_add_u32_e32 v48, 0x80, v116
	v_mad_i64_i32 v[48:49], s[12:13], v48, s35, v[112:113]
	v_lshl_add_u64 v[48:49], v[48:49], 0, v[114:115]
; __device__ __forceinline__ unsigned cvt_pk_bf16(float lo, float hi) { const f32x2 v = {lo, hi}; return __builtin_bit_cast(unsigned, __builtin_convertvector(v, bfx2_t)); }
;     __device__ __forceinline__ void operator()(const AccT& acc, const Unit& u, int ui, int wr, int wc, int fr, int fq) const {
;     ...
;                 const int rl = ai * 128 + wr * 64 + m * 16 + fr; const float r = rs[((u.pm >> 3) & 3) * 256 + rl];
;                 const float nr = -1.4426950408889634f * r, r2 = r * r;
;                 unsigned w[4];
; #pragma unroll
;                 for (int n = 0; n < 2; ++n)
; #pragma unroll
;                     for (int hlf = 0; hlf < 2; ++hlf) {
;                         const f32x2 a = {acc[ai][0][m][n][2 * hlf], acc[ai][0][m][n][2 * hlf + 1]}, b = {acc[ai][1][m][n][2 * hlf], acc[ai][1][m][n][2 * hlf + 1]};
;                         const f32x2 t = a * nr;
;                         f32x2 d; d.x = __builtin_amdgcn_exp2f(t.x); d.y = __builtin_amdgcn_exp2f(t.y); d = d + 1.0f;
;                         f32x2 q; q.x = __builtin_amdgcn_rcpf(d.x); q.y = __builtin_amdgcn_rcpf(d.y);
;                         const f32x2 o = ((a * b) * r2) * q;
;                         w[n * 2 + hlf] = cvt_pk_bf16(o.x, o.y);
;                     }
;                 u32x4 wv; wv.x = w[0]; wv.y = w[1]; wv.z = w[2]; wv.w = w[3];
;                 *GP(u32x4, O + (size_t)(u.pm * 256 + rl) * FF + col) = wv;
	global_store_dwordx4 v[48:49], v[56:59], off
	v_mul_f32_e32 v48, 0xbfb8aa3b, v65
	v_pk_mul_f32 v[52:53], v[40:41], v[48:49] op_sel_hi:[1,0]
	v_pk_mul_f32 v[42:43], v[42:43], v[48:49] op_sel_hi:[1,0]
	v_exp_f32_e32 v52, v52
	v_exp_f32_e32 v53, v53
	v_exp_f32_e32 v42, v42
	v_exp_f32_e32 v43, v43
	v_mul_f32_e32 v50, v65, v65
	v_pk_add_f32 v[52:53], v[52:53], 1.0 op_sel_hi:[1,0]
	v_pk_mul_f32 v[40:41], v[44:45], v[40:41]
	v_pk_add_f32 v[42:43], v[42:43], 1.0 op_sel_hi:[1,0]
	v_rcp_f32_e32 v52, v52
	v_rcp_f32_e32 v53, v53
	v_rcp_f32_e32 v42, v42
	v_rcp_f32_e32 v43, v43
	v_pk_mul_f32 v[40:41], v[40:41], v[50:51] op_sel_hi:[1,0]
	v_pk_mul_f32 v[44:45], v[46:47], v[50:51] op_sel_hi:[1,0]
	v_pk_mul_f32 v[40:41], v[40:41], v[52:53]
	v_pk_mul_f32 v[42:43], v[44:45], v[42:43]
	v_cvt_pk_bf16_f32 v40, v40, v41
	v_cvt_pk_bf16_f32 v41, v42, v43
	v_pk_mul_f32 v[42:43], v[32:33], v[48:49] op_sel_hi:[1,0]
	v_pk_mul_f32 v[32:33], v[36:37], v[32:33]
	v_exp_f32_e32 v42, v42
	v_exp_f32_e32 v43, v43
	v_pk_mul_f32 v[32:33], v[32:33], v[50:51] op_sel_hi:[1,0]
	v_pk_add_f32 v[42:43], v[42:43], 1.0 op_sel_hi:[1,0]
	s_nop 0
	v_rcp_f32_e32 v42, v42
	v_rcp_f32_e32 v43, v43
	s_nop 0
	v_pk_mul_f32 v[32:33], v[32:33], v[42:43]
	s_nop 0
	v_cvt_pk_bf16_f32 v42, v32, v33
	v_pk_mul_f32 v[32:33], v[34:35], v[48:49] op_sel_hi:[1,0]
	v_pk_mul_f32 v[34:35], v[38:39], v[50:51] op_sel_hi:[1,0]
	v_exp_f32_e32 v32, v32
	v_exp_f32_e32 v33, v33
	s_nop 0
	v_pk_add_f32 v[32:33], v[32:33], 1.0 op_sel_hi:[1,0]
	s_nop 0
	v_rcp_f32_e32 v32, v32
	v_rcp_f32_e32 v33, v33
	s_nop 0
	v_pk_mul_f32 v[32:33], v[34:35], v[32:33]
	s_nop 0
	v_cvt_pk_bf16_f32 v43, v32, v33
	v_add_u32_e32 v32, 0x90, v116
	v_mad_i64_i32 v[32:33], s[12:13], v32, s35, v[112:113]
	v_lshl_add_u64 v[32:33], v[32:33], 0, v[114:115]
	global_store_dwordx4 v[32:33], v[40:43], off
	v_mov_b32_e32 v32, v178
	v_mov_b32_e32 v33, v179
	s_waitcnt lgkmcnt(0)
	v_mul_f32_e32 v34, 0xbfb8aa3b, v32
	v_pk_mul_f32 v[36:37], v[24:25], v[34:35] op_sel_hi:[1,0]
	v_pk_mul_f32 v[26:27], v[26:27], v[34:35] op_sel_hi:[1,0]
	v_exp_f32_e32 v36, v36
	v_exp_f32_e32 v37, v37
	v_exp_f32_e32 v26, v26
	v_exp_f32_e32 v27, v27
	v_mul_f32_e32 v32, v32, v32
	v_pk_add_f32 v[36:37], v[36:37], 1.0 op_sel_hi:[1,0]
	v_pk_mul_f32 v[24:25], v[28:29], v[24:25]
	v_pk_add_f32 v[26:27], v[26:27], 1.0 op_sel_hi:[1,0]
	v_rcp_f32_e32 v36, v36
	v_rcp_f32_e32 v37, v37
	v_rcp_f32_e32 v26, v26
	v_rcp_f32_e32 v27, v27
	v_pk_mul_f32 v[24:25], v[24:25], v[32:33] op_sel_hi:[1,0]
	v_pk_mul_f32 v[28:29], v[30:31], v[32:33] op_sel_hi:[1,0]
	v_pk_mul_f32 v[24:25], v[24:25], v[36:37]
	v_pk_mul_f32 v[26:27], v[28:29], v[26:27]
	v_cvt_pk_bf16_f32 v24, v24, v25
	v_cvt_pk_bf16_f32 v25, v26, v27
	v_pk_mul_f32 v[26:27], v[16:17], v[34:35] op_sel_hi:[1,0]
	v_pk_mul_f32 v[16:17], v[20:21], v[16:17]
	v_exp_f32_e32 v26, v26
	v_exp_f32_e32 v27, v27
	v_pk_mul_f32 v[16:17], v[16:17], v[32:33] op_sel_hi:[1,0]
	v_pk_add_f32 v[26:27], v[26:27], 1.0 op_sel_hi:[1,0]
	s_nop 0
	v_rcp_f32_e32 v26, v26
	v_rcp_f32_e32 v27, v27
	s_nop 0
	v_pk_mul_f32 v[16:17], v[16:17], v[26:27]
	s_nop 0
	v_cvt_pk_bf16_f32 v26, v16, v17
	v_pk_mul_f32 v[16:17], v[18:19], v[34:35] op_sel_hi:[1,0]
	v_pk_mul_f32 v[18:19], v[22:23], v[32:33] op_sel_hi:[1,0]
	v_exp_f32_e32 v16, v16
	v_exp_f32_e32 v17, v17
	s_nop 0
	v_pk_add_f32 v[16:17], v[16:17], 1.0 op_sel_hi:[1,0]
	s_nop 0
	v_rcp_f32_e32 v16, v16
	v_rcp_f32_e32 v17, v17
	s_nop 0
	v_pk_mul_f32 v[16:17], v[18:19], v[16:17]
	s_nop 0
	v_cvt_pk_bf16_f32 v27, v16, v17
	v_add_u32_e32 v16, 0xa0, v116
	v_mad_i64_i32 v[16:17], s[12:13], v16, s35, v[112:113]
	v_lshl_add_u64 v[16:17], v[16:17], 0, v[114:115]
	global_store_dwordx4 v[16:17], v[24:27], off
	v_mul_f32_e32 v16, 0xbfb8aa3b, v33
	v_pk_mul_f32 v[20:21], v[8:9], v[16:17] op_sel_hi:[1,0]
	v_pk_mul_f32 v[10:11], v[10:11], v[16:17] op_sel_hi:[1,0]
	v_exp_f32_e32 v20, v20
	v_exp_f32_e32 v21, v21
	v_exp_f32_e32 v10, v10
	v_exp_f32_e32 v11, v11
	v_mul_f32_e32 v18, v33, v33
	v_pk_add_f32 v[20:21], v[20:21], 1.0 op_sel_hi:[1,0]
	v_pk_mul_f32 v[8:9], v[12:13], v[8:9]
	v_pk_add_f32 v[10:11], v[10:11], 1.0 op_sel_hi:[1,0]
	v_rcp_f32_e32 v20, v20
	v_rcp_f32_e32 v21, v21
	v_rcp_f32_e32 v10, v10
	v_rcp_f32_e32 v11, v11
	v_pk_mul_f32 v[8:9], v[8:9], v[18:19] op_sel_hi:[1,0]
	v_pk_mul_f32 v[12:13], v[14:15], v[18:19] op_sel_hi:[1,0]
	v_pk_mul_f32 v[8:9], v[8:9], v[20:21]
	v_pk_mul_f32 v[10:11], v[12:13], v[10:11]
	v_cvt_pk_bf16_f32 v8, v8, v9
	v_cvt_pk_bf16_f32 v9, v10, v11
	v_pk_mul_f32 v[10:11], v[0:1], v[16:17] op_sel_hi:[1,0]
	v_pk_mul_f32 v[0:1], v[4:5], v[0:1]
	v_exp_f32_e32 v10, v10
	v_exp_f32_e32 v11, v11
	v_pk_mul_f32 v[0:1], v[0:1], v[18:19] op_sel_hi:[1,0]
	v_pk_add_f32 v[10:11], v[10:11], 1.0 op_sel_hi:[1,0]
	s_nop 0
	v_rcp_f32_e32 v10, v10
	v_rcp_f32_e32 v11, v11
	s_nop 0
	v_pk_mul_f32 v[0:1], v[0:1], v[10:11]
	s_nop 0
	v_cvt_pk_bf16_f32 v10, v0, v1
	v_pk_mul_f32 v[0:1], v[2:3], v[16:17] op_sel_hi:[1,0]
	v_pk_mul_f32 v[2:3], v[6:7], v[18:19] op_sel_hi:[1,0]
	v_exp_f32_e32 v0, v0
	v_exp_f32_e32 v1, v1
	s_nop 0
	v_pk_add_f32 v[0:1], v[0:1], 1.0 op_sel_hi:[1,0]
	s_nop 0
	v_rcp_f32_e32 v0, v0
	v_rcp_f32_e32 v1, v1
	s_nop 0
	v_pk_mul_f32 v[0:1], v[2:3], v[0:1]
	s_nop 0
	v_cvt_pk_bf16_f32 v11, v0, v1
	v_add_u32_e32 v0, 0xb0, v116
	v_mad_i64_i32 v[0:1], s[12:13], v0, s35, v[112:113]
	v_lshl_add_u64 v[0:1], v[0:1], 0, v[114:115]
	global_store_dwordx4 v[0:1], v[8:11], off
	s_cbranch_vccnz .LBB0_614

; template <class Epi, class Ord>
; __device__ __forceinline__ void gemm_phase(LAS unsigned char* lds, const Gemm g, const Ord& S, const Epi& E) {
;     ...
; #pragma unroll
;         for (int a = 0; a < 2; ++a)
; #pragma unroll
;             for (int b = 0; b < 2; ++b)
; #pragma unroll
;                 for (int m = 0; m < 4; ++m)
; #pragma unroll
;                     for (int n = 0; n < 2; ++n) acc[a][b][m][n] = (f32x4){0.f, 0.f, 0.f, 0.f};
;         cur = nxt; cA = nA; cB = nB; ++ui;
.LBB0_611:
	v_mov_b32_e32 v123, 0
	v_mov_b32_e32 v122, 0
	s_andn2_b64 vcc, exec, s[16:17]
	v_pk_mov_b32 v[120:121], v[122:123], v[122:123]
	v_pk_mov_b32 v[114:115], v[122:123], v[122:123]
	v_pk_mov_b32 v[112:113], v[122:123], v[122:123]
	v_pk_mov_b32 v[106:107], v[122:123], v[122:123]
	v_pk_mov_b32 v[104:105], v[122:123], v[122:123]
	v_pk_mov_b32 v[98:99], v[122:123], v[122:123]
	v_pk_mov_b32 v[96:97], v[122:123], v[122:123]
	v_pk_mov_b32 v[90:91], v[122:123], v[122:123]
	v_pk_mov_b32 v[88:89], v[122:123], v[122:123]
	v_pk_mov_b32 v[82:83], v[122:123], v[122:123]
	v_pk_mov_b32 v[80:81], v[122:123], v[122:123]
	v_pk_mov_b32 v[74:75], v[122:123], v[122:123]
	v_pk_mov_b32 v[72:73], v[122:123], v[122:123]
	v_pk_mov_b32 v[66:67], v[122:123], v[122:123]
	v_pk_mov_b32 v[64:65], v[122:123], v[122:123]
	v_pk_mov_b32 v[126:127], v[122:123], v[122:123]
	v_pk_mov_b32 v[124:125], v[122:123], v[122:123]
	v_pk_mov_b32 v[118:119], v[122:123], v[122:123]
	v_pk_mov_b32 v[116:117], v[122:123], v[122:123]
	v_pk_mov_b32 v[110:111], v[122:123], v[122:123]
	v_pk_mov_b32 v[108:109], v[122:123], v[122:123]
	v_pk_mov_b32 v[102:103], v[122:123], v[122:123]
	v_pk_mov_b32 v[100:101], v[122:123], v[122:123]
	v_pk_mov_b32 v[94:95], v[122:123], v[122:123]
	v_pk_mov_b32 v[92:93], v[122:123], v[122:123]
	v_pk_mov_b32 v[86:87], v[122:123], v[122:123]
	v_pk_mov_b32 v[84:85], v[122:123], v[122:123]
	v_pk_mov_b32 v[78:79], v[122:123], v[122:123]
	v_pk_mov_b32 v[76:77], v[122:123], v[122:123]
	v_pk_mov_b32 v[70:71], v[122:123], v[122:123]
	v_pk_mov_b32 v[68:69], v[122:123], v[122:123]
	v_pk_mov_b32 v[58:59], v[122:123], v[122:123]
	v_pk_mov_b32 v[56:57], v[122:123], v[122:123]
	v_pk_mov_b32 v[50:51], v[122:123], v[122:123]
	v_pk_mov_b32 v[48:49], v[122:123], v[122:123]
	v_pk_mov_b32 v[42:43], v[122:123], v[122:123]
	v_pk_mov_b32 v[40:41], v[122:123], v[122:123]
	v_pk_mov_b32 v[34:35], v[122:123], v[122:123]
	v_pk_mov_b32 v[32:33], v[122:123], v[122:123]
	v_pk_mov_b32 v[26:27], v[122:123], v[122:123]
	v_pk_mov_b32 v[24:25], v[122:123], v[122:123]
	v_pk_mov_b32 v[18:19], v[122:123], v[122:123]
	v_pk_mov_b32 v[16:17], v[122:123], v[122:123]
	v_pk_mov_b32 v[10:11], v[122:123], v[122:123]
	v_pk_mov_b32 v[8:9], v[122:123], v[122:123]
	v_pk_mov_b32 v[2:3], v[122:123], v[122:123]
	v_pk_mov_b32 v[0:1], v[122:123], v[122:123]
	v_pk_mov_b32 v[62:63], v[122:123], v[122:123]
	v_pk_mov_b32 v[60:61], v[122:123], v[122:123]
	v_pk_mov_b32 v[54:55], v[122:123], v[122:123]
	v_pk_mov_b32 v[52:53], v[122:123], v[122:123]
	v_pk_mov_b32 v[46:47], v[122:123], v[122:123]
	v_pk_mov_b32 v[44:45], v[122:123], v[122:123]
	v_pk_mov_b32 v[38:39], v[122:123], v[122:123]
	v_pk_mov_b32 v[36:37], v[122:123], v[122:123]
	v_pk_mov_b32 v[30:31], v[122:123], v[122:123]
	v_pk_mov_b32 v[28:29], v[122:123], v[122:123]
	v_pk_mov_b32 v[22:23], v[122:123], v[122:123]
	v_pk_mov_b32 v[20:21], v[122:123], v[122:123]
	v_pk_mov_b32 v[14:15], v[122:123], v[122:123]
	v_pk_mov_b32 v[12:13], v[122:123], v[122:123]
	v_pk_mov_b32 v[6:7], v[122:123], v[122:123]
	v_pk_mov_b32 v[4:5], v[122:123], v[122:123]
	s_cbranch_vccnz .LBB0_603
	s_add_u32 s44, s44, 0x100
	s_addc_u32 s45, s45, 0
	s_add_u32 s46, s46, 0x100
	v_mov_b32_e32 v4, 0
	v_mov_b32_e32 v5, 0
	s_addc_u32 s47, s47, 0
	s_mov_b32 s12, 0
	v_pk_mov_b32 v[6:7], v[4:5], v[4:5]
	v_pk_mov_b32 v[12:13], v[4:5], v[4:5]
	v_pk_mov_b32 v[14:15], v[4:5], v[4:5]
	v_pk_mov_b32 v[20:21], v[4:5], v[4:5]
	v_pk_mov_b32 v[22:23], v[4:5], v[4:5]
	v_pk_mov_b32 v[28:29], v[4:5], v[4:5]
	v_pk_mov_b32 v[30:31], v[4:5], v[4:5]
	v_pk_mov_b32 v[36:37], v[4:5], v[4:5]
	v_pk_mov_b32 v[38:39], v[4:5], v[4:5]
	v_pk_mov_b32 v[44:45], v[4:5], v[4:5]
	v_pk_mov_b32 v[46:47], v[4:5], v[4:5]
	v_pk_mov_b32 v[52:53], v[4:5], v[4:5]
	v_pk_mov_b32 v[54:55], v[4:5], v[4:5]
	v_pk_mov_b32 v[60:61], v[4:5], v[4:5]
	v_pk_mov_b32 v[62:63], v[4:5], v[4:5]
	v_pk_mov_b32 v[0:1], v[4:5], v[4:5]
	v_pk_mov_b32 v[2:3], v[4:5], v[4:5]
	v_pk_mov_b32 v[8:9], v[4:5], v[4:5]
	v_pk_mov_b32 v[10:11], v[4:5], v[4:5]
	v_pk_mov_b32 v[16:17], v[4:5], v[4:5]
	v_pk_mov_b32 v[18:19], v[4:5], v[4:5]
	v_pk_mov_b32 v[24:25], v[4:5], v[4:5]
	v_pk_mov_b32 v[26:27], v[4:5], v[4:5]
	v_pk_mov_b32 v[32:33], v[4:5], v[4:5]
	v_pk_mov_b32 v[34:35], v[4:5], v[4:5]
	v_pk_mov_b32 v[40:41], v[4:5], v[4:5]
	v_pk_mov_b32 v[42:43], v[4:5], v[4:5]
	v_pk_mov_b32 v[48:49], v[4:5], v[4:5]
	v_pk_mov_b32 v[50:51], v[4:5], v[4:5]
	v_pk_mov_b32 v[56:57], v[4:5], v[4:5]
	v_pk_mov_b32 v[58:59], v[4:5], v[4:5]
	v_pk_mov_b32 v[68:69], v[4:5], v[4:5]
	v_pk_mov_b32 v[70:71], v[4:5], v[4:5]
	v_pk_mov_b32 v[76:77], v[4:5], v[4:5]
	v_pk_mov_b32 v[78:79], v[4:5], v[4:5]
	v_pk_mov_b32 v[84:85], v[4:5], v[4:5]
	v_pk_mov_b32 v[86:87], v[4:5], v[4:5]
	v_pk_mov_b32 v[92:93], v[4:5], v[4:5]
	v_pk_mov_b32 v[94:95], v[4:5], v[4:5]
	v_pk_mov_b32 v[100:101], v[4:5], v[4:5]
	v_pk_mov_b32 v[102:103], v[4:5], v[4:5]
	v_pk_mov_b32 v[108:109], v[4:5], v[4:5]
	v_pk_mov_b32 v[110:111], v[4:5], v[4:5]
	v_pk_mov_b32 v[116:117], v[4:5], v[4:5]
	v_pk_mov_b32 v[118:119], v[4:5], v[4:5]
	v_pk_mov_b32 v[124:125], v[4:5], v[4:5]
	v_pk_mov_b32 v[126:127], v[4:5], v[4:5]
	v_pk_mov_b32 v[64:65], v[4:5], v[4:5]
	v_pk_mov_b32 v[66:67], v[4:5], v[4:5]
	v_pk_mov_b32 v[72:73], v[4:5], v[4:5]
	v_pk_mov_b32 v[74:75], v[4:5], v[4:5]
	v_pk_mov_b32 v[80:81], v[4:5], v[4:5]
	v_pk_mov_b32 v[82:83], v[4:5], v[4:5]
	v_pk_mov_b32 v[88:89], v[4:5], v[4:5]
	v_pk_mov_b32 v[90:91], v[4:5], v[4:5]
	v_pk_mov_b32 v[96:97], v[4:5], v[4:5]
	v_pk_mov_b32 v[98:99], v[4:5], v[4:5]
	v_pk_mov_b32 v[104:105], v[4:5], v[4:5]
	v_pk_mov_b32 v[106:107], v[4:5], v[4:5]
	v_pk_mov_b32 v[112:113], v[4:5], v[4:5]
	v_pk_mov_b32 v[114:115], v[4:5], v[4:5]
	v_pk_mov_b32 v[120:121], v[4:5], v[4:5]
	v_pk_mov_b32 v[122:123], v[4:5], v[4:5]
